# sample-tile gMLP spatial weights (mode 1) also stored in MFMA-fragment order and read as contiguous 1 KiB fragments by the P6 gMLP copy
# baseline (speedup 1.0000x reference)
; __device__ __forceinline__ bf16 f2bf(float f) { return (bf16)(cvt_pk_nv(f, 0.f) & 0xffffu); }
;     __device__ __forceinline__ const float* in(int i) const { return karg_in(i); }
; __device__ __forceinline__ void p0_prologue(const Ctx& C, LAS unsigned char* lds, int wave, int lane, int tid) {
;     ...
;     for (int idx = gt; idx < 2 * 4 * 128 * 128; idx += NGT) {
;         const int s = idx & 127, t = (idx >> 7) & 127, h = (idx >> 14) & 3, mode = idx >> 16;
;         float v;
;         if (mode == 0) v = (s <= t) ? C.in(12)[((size_t)h * 128 + t) * 128 + s] : 0.f;
;         else v = ((s >> 4) == (t >> 4) && (s & 15) <= (t & 15)) ? C.in(12)[((size_t)h * 128 + (t & 15)) * 128 + (s & 15)] : 0.f;
;         C.Weff()[idx] = f2bf(v);
;     }
.LBB0_131:
	s_or_b64 exec, exec, s[16:17]
	s_mov_b64 s[0:1], s[80:81]
	s_load_dwordx2 s[0:1], s[0:1], 0x110
	v_add_u32_e32 v0, s6, v0
	v_cmp_lt_i32_e32 vcc, s10, v0
	s_or_b64 s[12:13], vcc, s[12:13]
	s_waitcnt vmcnt(0)
	v_cvt_pk_bf16_f32 v1, v1, v5
	s_waitcnt lgkmcnt(0)
	v_and_b32_e32 v46, 0x3ffff, v2
	v_and_b32_e32 v47, 0x3e00e, v46
	v_bfe_u32 v48, v46, 8, 5
	v_lshl_or_b32 v47, v48, 4, v47
	v_bfe_u32 v48, v46, 4, 1
	v_lshl_or_b32 v47, v48, 9, v47
	v_bfe_u32 v48, v46, 5, 3
	v_lshl_or_b32 v47, v48, 10, v47
	v_add_u32_e32 v46, 0x2900000, v47
	v_mov_b32_e32 v47, 0
	v_lshl_add_u64 v[6:7], s[0:1], 0, v[46:47]
	v_lshl_add_u64 v[2:3], v[2:3], 0, s[8:9]
	global_store_short v[6:7], v1, off
	s_andn2_b64 exec, exec, s[12:13]
	s_cbranch_execz .LBB0_144

; __device__ __forceinline__ float bf_lo(unsigned w) { return __uint_as_float(w << 16); }
; __device__ __forceinline__ float bf_hi(unsigned w) { return __uint_as_float(w & 0xffff0000u); }
;     __device__ __forceinline__ const float* in(int i) const { return karg_in(i); }
; __device__ __forceinline__ void gmlp_tile(const Ctx& C, int T, LAS unsigned char* lds, int wave, int lane, int tid) {
;     ...
;     const bf16* zt = C.Z() + (size_t)(r0 + t) * DIN;
;     const int row = tid >> 2, q = tid & 3;
;     const bf16* vsrc = C.Z() + (size_t)(r0 + row) * DIN + 512 + q * 32;
;     const bf16* Weff = C.Weff();
;     v4u vraw[4];
; #pragma unroll
;     for (int i = 0; i < 4; ++i) vraw[i] = *(const v4u*)(vsrc + 8 * i);
; #pragma unroll
;     for (int h = 0; h < 4; ++h) {
;         bfx8 wf[8];
;         const bf16* wrow = Weff + ((size_t)(mode * 4 + h) * 128 + t) * 128 + 8 * hh;
; #pragma unroll
;         for (int ks = 0; ks < 8; ++ks) wf[ks] = *(const bfx8*)(wrow + 16 * ks);
;         v2u uw[2][4];
; #pragma unroll
;         for (int dbi = 0; dbi < 2; ++dbi)
; #pragma unroll
;             for (int rg = 0; rg < 4; ++rg) uw[dbi][rg] = *(const v2u*)(zt + h * 128 + 32 * (2 * dh + dbi) + 8 * rg + 4 * hh);
;         const float bias = C.in(13)[h * 128 + (mode ? (t & 15) : t)];
;         v4f gvv[8];
;         { const float* gvp = C.in(11) + h * 128 + q * 32;
; #pragma unroll
;           for (int i = 0; i < 8; ++i) gvv[i] = *(const v4f*)(gvp + 4 * i); }
;         __syncthreads();
;         {
;             float v[32]; float s = 0.f;
; #pragma unroll
;             for (int i = 0; i < 4; ++i) { const v4u w = vraw[i];
;                 v[8 * i + 0] = bf_lo(w.x); v[8 * i + 1] = bf_hi(w.x); v[8 * i + 2] = bf_lo(w.y); v[8 * i + 3] = bf_hi(w.y);
;                 v[8 * i + 4] = bf_lo(w.z); v[8 * i + 5] = bf_hi(w.z); v[8 * i + 6] = bf_lo(w.w); v[8 * i + 7] = bf_hi(w.w); }
;             if (h < 3) {
; #pragma unroll
;                 for (int i = 0; i < 4; ++i) vraw[i] = *(const v4u*)(vsrc + (h + 1) * 128 + 8 * i);
;             }
; #pragma unroll
;             for (int i = 0; i < 32; ++i) s += v[i] * v[i];
;             s += __shfl_xor(s, 1); s += __shfl_xor(s, 2);
.LBB0_680:
	s_cmp_lg_u32 s33, 0
	s_cbranch_scc1 .LBB0_686
	s_mov_b64 s[0:1], s[80:81]
	s_barrier
	s_mov_b64 s[10:11], s[80:81]
	s_load_dwordx2 s[0:1], s[0:1], 0x110
	s_load_dwordx2 s[10:11], s[10:11], 0x110
	v_ashrrev_i32_e32 v8, 2, v160
	s_movk_i32 s3, 0xc00
	v_add_u32_e32 v2, 0x8000, v8
	s_waitcnt vmcnt(11)
	v_mov_b32_e32 v77, 0
	s_waitcnt lgkmcnt(0)
	v_mov_b64_e32 v[0:1], s[10:11]
	v_mad_i64_i32 v[0:1], s[10:11], v2, s3, v[0:1]
	v_lshlrev_b32_e32 v2, 5, v160
	v_and_b32_e32 v9, 0x60, v2
	v_lshlrev_b32_e32 v76, 1, v9
	v_lshl_add_u64 v[0:1], v[0:1], 0, v[76:77]
	s_mov_b64 s[10:11], 0xb200400
	s_mov_b32 s3, 0xb200000
	v_lshl_add_u64 v[84:85], v[0:1], 0, s[10:11]
	v_add_co_u32_e32 v0, vcc, s3, v0
	s_mov_b64 s[10:11], s[80:81]
	s_nop 0
	v_addc_co_u32_e32 v1, vcc, 0, v1, vcc
	global_load_dwordx4 v[14:17], v[84:85], off offset:48
	global_load_dwordx4 v[18:21], v[0:1], off offset:1024
	s_load_dwordx2 s[10:11], s[10:11], 0x110
	global_load_dwordx4 v[22:25], v[84:85], off offset:32
	global_load_dwordx4 v[26:29], v[84:85], off offset:16
	v_readfirstlane_b32 s3, v160
	s_ashr_i32 s14, s3, 6
	s_lshl_b32 s12, s14, 5
	v_and_b32_e32 v152, 31, v160
	s_and_b32 s12, s12, 0x60
	v_or_b32_e32 v109, s12, v152
	v_mul_u32_u24_e32 v0, 0xc00, v109
	v_bfe_u32 v153, v160, 5, 1
	v_mov_b32_e32 v1, v77
	s_ashr_i32 s15, s3, 8
	v_lshl_add_u64 v[0:1], s[0:1], 0, v[0:1]
	v_lshlrev_b32_e32 v76, 3, v153
	v_lshlrev_b32_e32 v6, 4, v153
	v_mov_b32_e32 v7, v77
	s_waitcnt lgkmcnt(0)
	v_lshl_add_u64 v[2:3], s[10:11], 0, v[6:7]
	s_lshl_b32 s10, s15, 6
	v_lshl_add_u64 v[4:5], v[0:1], 0, v[76:77]
	v_lshlrev_b32_e32 v76, 8, v109
	v_lshl_add_u64 v[78:79], v[2:3], 0, v[76:77]
	v_mul_u32_u24_e32 v234, 0x1f0, v153
	v_mul_u32_u24_e32 v235, 0xf0, v152
	v_sub_u32_e32 v234, v234, v235
	v_add_u32_e32 v234, 0xe00, v234
	v_ashrrev_i32_e32 v235, 31, v234
	v_lshl_add_u64 v[78:79], v[234:235], 0, v[78:79]
	s_mov_b32 s0, 0x2920000
	s_ashr_i32 s11, s10, 31
	v_add_co_u32_e32 v10, vcc, s0, v78
	v_lshl_add_u64 v[4:5], s[10:11], 1, v[4:5]
	s_mov_b64 s[0:1], 0x11200000
	v_addc_co_u32_e32 v11, vcc, 0, v79, vcc
	v_lshl_add_u64 v[80:81], v[4:5], 0, s[0:1]
	s_mov_b32 s0, 0x11200000
	global_load_dwordx4 v[0:3], v[10:11], off offset:-3584
	global_load_dwordx4 v[64:67], v[10:11], off offset:-2560
	global_load_dwordx4 v[60:63], v[10:11], off offset:-1536
	global_load_dwordx4 v[56:59], v[10:11], off offset:-512
	global_load_dwordx4 v[48:51], v[10:11], off offset:512
	global_load_dwordx4 v[44:47], v[10:11], off offset:1536
	global_load_dwordx4 v[40:43], v[10:11], off offset:2560
	global_load_dwordx4 v[32:35], v[10:11], off offset:3584
	v_add_co_u32_e32 v10, vcc, s0, v4
	s_mov_b64 s[0:1], s[80:81]
	s_nop 0
	v_addc_co_u32_e32 v11, vcc, 0, v5, vcc
	global_load_dwordx2 v[4:5], v[80:81], off offset:16
	global_load_dwordx2 v[72:73], v[80:81], off offset:32
	global_load_dwordx2 v[70:71], v[80:81], off offset:48
	global_load_dwordx2 v[68:69], v[80:81], off offset:64
	global_load_dwordx2 v[74:75], v[10:11], off
	global_load_dwordx2 v[96:97], v[80:81], off offset:80
	global_load_dwordx2 v[92:93], v[80:81], off offset:96
	global_load_dwordx2 v[88:89], v[80:81], off offset:112
	s_load_dwordx2 s[0:1], s[0:1], 0x68
	v_and_b32_e32 v7, 15, v160
	v_lshlrev_b32_e32 v124, 2, v7
	v_lshlrev_b32_e32 v76, 2, v9
	s_mov_b32 s11, 0x800000
	s_waitcnt lgkmcnt(0)
	global_load_dword v125, v124, s[0:1]
	s_mov_b64 s[0:1], s[80:81]
	s_load_dwordx2 s[12:13], s[0:1], 0x58
	s_waitcnt lgkmcnt(0)
	global_load_dwordx4 v[98:101], v76, s[12:13] offset:48
	global_load_dwordx4 v[102:105], v76, s[12:13] offset:32
	global_load_dwordx4 v[112:115], v76, s[12:13] offset:16
	global_load_dwordx4 v[116:119], v76, s[12:13]
	global_load_dwordx4 v[126:129], v76, s[12:13] offset:80
	global_load_dwordx4 v[130:133], v76, s[12:13] offset:64
	v_lshlrev_b32_e32 v108, 1, v8
	v_mul_u32_u24_e32 v9, 0x110, v9
	s_mov_b64 s[0:1], s[80:81]
	s_movk_i32 s3, 0x110
	s_mov_b32 s16, 0x80a8000
	s_waitcnt vmcnt(26)
	v_lshlrev_b32_e32 v146, 16, v14
	s_waitcnt vmcnt(25)
	v_lshlrev_b32_e32 v82, 16, v18
	v_and_b32_e32 v83, 0xffff0000, v18
	v_pk_mul_f32 v[36:37], v[82:83], v[82:83]
	v_lshlrev_b32_e32 v86, 16, v19
	v_and_b32_e32 v87, 0xffff0000, v19
	v_pk_mul_f32 v[18:19], v[86:87], v[86:87]
	v_add_f32_e32 v7, v36, v37
	v_lshlrev_b32_e32 v90, 16, v20
	v_and_b32_e32 v91, 0xffff0000, v20
	v_add_f32_e32 v7, v18, v7
	v_pk_mul_f32 v[38:39], v[90:91], v[90:91]
	v_add_f32_e32 v7, v19, v7
	v_lshlrev_b32_e32 v94, 16, v21
	v_and_b32_e32 v95, 0xffff0000, v21
	v_add_f32_e32 v7, v38, v7
	v_pk_mul_f32 v[20:21], v[94:95], v[94:95]
	v_add_f32_e32 v7, v39, v7
	s_waitcnt vmcnt(23)
	v_lshlrev_b32_e32 v106, 16, v26
	v_and_b32_e32 v107, 0xffff0000, v26
	v_add_f32_e32 v7, v20, v7
	v_pk_mul_f32 v[52:53], v[106:107], v[106:107]
	v_add_f32_e32 v7, v21, v7
	v_lshlrev_b32_e32 v120, 16, v27
	v_and_b32_e32 v121, 0xffff0000, v27
	v_add_f32_e32 v7, v52, v7
	v_pk_mul_f32 v[26:27], v[120:121], v[120:121]
	v_add_f32_e32 v7, v53, v7
	v_lshlrev_b32_e32 v134, 16, v28
	v_and_b32_e32 v135, 0xffff0000, v28
	v_add_f32_e32 v7, v26, v7
	v_pk_mul_f32 v[54:55], v[134:135], v[134:135]
	v_add_f32_e32 v7, v27, v7
	v_lshlrev_b32_e32 v136, 16, v29
	v_and_b32_e32 v137, 0xffff0000, v29
	v_add_f32_e32 v7, v54, v7
	v_pk_mul_f32 v[28:29], v[136:137], v[136:137]
	v_add_f32_e32 v7, v55, v7
	v_lshlrev_b32_e32 v138, 16, v22
	v_and_b32_e32 v139, 0xffff0000, v22
	v_add_f32_e32 v7, v28, v7
	v_pk_mul_f32 v[110:111], v[138:139], v[138:139]
	v_add_f32_e32 v7, v29, v7
	v_lshlrev_b32_e32 v22, 16, v23
	v_and_b32_e32 v23, 0xffff0000, v23
	v_add_f32_e32 v7, v110, v7
	v_pk_mul_f32 v[122:123], v[22:23], v[22:23]
	v_add_f32_e32 v7, v111, v7
	v_lshlrev_b32_e32 v140, 16, v24
	v_and_b32_e32 v141, 0xffff0000, v24
	v_add_f32_e32 v7, v122, v7
	v_pk_mul_f32 v[142:143], v[140:141], v[140:141]
	v_add_f32_e32 v7, v123, v7
	v_lshlrev_b32_e32 v144, 16, v25
	v_and_b32_e32 v145, 0xffff0000, v25
	v_add_f32_e32 v7, v142, v7
	v_pk_mul_f32 v[24:25], v[144:145], v[144:145]
	v_add_f32_e32 v7, v143, v7
	v_and_b32_e32 v147, 0xffff0000, v14
	v_add_f32_e32 v7, v24, v7
	v_pk_mul_f32 v[148:149], v[146:147], v[146:147]
	v_add_f32_e32 v7, v25, v7
	v_lshlrev_b32_e32 v150, 16, v15
	v_and_b32_e32 v151, 0xffff0000, v15
	v_add_f32_e32 v7, v148, v7
	v_pk_mul_f32 v[14:15], v[150:151], v[150:151]
	v_add_f32_e32 v7, v149, v7
	v_and_b32_e32 v12, 0xffff0000, v16
	v_lshlrev_b32_e32 v13, 16, v16
	v_add_f32_e32 v7, v14, v7
	v_pk_mul_f32 v[30:31], v[12:13], v[12:13]
	v_add_f32_e32 v7, v15, v7
	v_and_b32_e32 v10, 0xffff0000, v17
	v_lshlrev_b32_e32 v11, 16, v17
	v_add_f32_e32 v7, v31, v7
	v_pk_mul_f32 v[16:17], v[10:11], v[10:11]
	v_add_f32_e32 v7, v30, v7
	v_add_f32_e32 v7, v17, v7
	v_add_f32_e32 v7, v16, v7
	global_load_dwordx4 v[14:17], v76, s[12:13] offset:112
	global_load_dwordx4 v[18:21], v76, s[12:13] offset:96
	ds_bpermute_b32 v24, v183, v7
	v_mov_b32_e32 v110, 0x358637bd
	v_add3_u32 v123, 0, v108, v9
	s_waitcnt lgkmcnt(0)
	s_barrier
; __device__ __forceinline__ float bf_lo(unsigned w) { return __uint_as_float(w << 16); }
; __device__ __forceinline__ float bf_hi(unsigned w) { return __uint_as_float(w & 0xffff0000u); }
; __device__ __forceinline__ bf16 f2bf(float f) { return (bf16)(cvt_pk_nv(f, 0.f) & 0xffffu); }
;     __device__ __forceinline__ float* out() const { return (float*)karg_in(33); }
; __device__ __forceinline__ void gmlp_tile(const Ctx& C, int T, LAS unsigned char* lds, int wave, int lane, int tid) {
;     ...
;         {
;             float v[32]; float s = 0.f;
; #pragma unroll
;             for (int i = 0; i < 4; ++i) { const v4u w = vraw[i];
;                 v[8 * i + 0] = bf_lo(w.x); v[8 * i + 1] = bf_hi(w.x); v[8 * i + 2] = bf_lo(w.y); v[8 * i + 3] = bf_hi(w.y);
;                 v[8 * i + 4] = bf_lo(w.z); v[8 * i + 5] = bf_hi(w.z); v[8 * i + 6] = bf_lo(w.w); v[8 * i + 7] = bf_hi(w.w); }
;             if (h < 3) {
; #pragma unroll
;                 for (int i = 0; i < 4; ++i) vraw[i] = *(const v4u*)(vsrc + (h + 1) * 128 + 8 * i);
;             }
; #pragma unroll
;             for (int i = 0; i < 32; ++i) s += v[i] * v[i];
;             s += __shfl_xor(s, 1); s += __shfl_xor(s, 2);
;             const float r = rsqrtf(s * (1.f / 128.f) + EPS);
; #pragma unroll
;             for (int i = 0; i < 32; ++i) { v[i] = v[i] * r * gvv[i >> 2][i & 3]; VT[(q * 32 + i) * VT_STRIDE + row] = f2bf(v[i]); }
;             if (mode) { float* ov = C.out() + OFF_V_S + (size_t)row * AW + h * 128 + q * 32;
; #pragma unroll
;                 for (int i = 0; i < 8; ++i) *(v4f*)(ov + 4 * i) = (v4f){v[4 * i], v[4 * i + 1], v[4 * i + 2], v[4 * i + 3]}; }
;         }
;         __syncthreads();
	v_add_f32_e32 v7, v7, v24
	ds_bpermute_b32 v36, v184, v7
	s_waitcnt lgkmcnt(0)
	global_load_dwordx4 v[24:27], v[84:85], off offset:304
	global_load_dwordx4 v[28:31], v[84:85], off offset:288
	s_waitcnt vmcnt(13)
	v_lshlrev_b32_e32 v189, 16, v96
	v_add_f32_e32 v7, v7, v36
	v_fmamk_f32 v7, v7, 0x3c000000, v110
	v_mul_f32_e32 v36, 0x4b800000, v7
	v_cmp_gt_f32_e32 vcc, s11, v7
	s_waitcnt vmcnt(1)
	v_lshlrev_b32_e32 v178, 16, v24
	v_cndmask_b32_e32 v7, v7, v36, vcc
	v_rsq_f32_e32 v7, v7
	global_load_dwordx4 v[36:39], v[84:85], off offset:272
	global_load_dwordx4 v[52:55], v[84:85], off offset:256
	s_waitcnt vmcnt(2)
	v_lshlrev_b32_e32 v166, 16, v28
	v_and_b32_e32 v167, 0xffff0000, v28
	v_mul_f32_e32 v9, 0x45800000, v7
	v_cndmask_b32_e32 v108, v7, v9, vcc
	v_pk_mul_f32 v[82:83], v[108:109], v[82:83] op_sel_hi:[0,1]
	v_pk_mul_f32 v[116:117], v[116:117], v[82:83]
	v_pk_mul_f32 v[82:83], v[108:109], v[86:87] op_sel_hi:[0,1]
	v_cvt_pk_bf16_f32 v7, v116, v77
	ds_write_b16 v123, v7
	v_cvt_pk_bf16_f32 v7, v117, v77
	ds_write_b16 v123, v7 offset:272
	v_pk_mul_f32 v[118:119], v[118:119], v[82:83]
	v_pk_mul_f32 v[82:83], v[108:109], v[90:91] op_sel_hi:[0,1]
	v_cvt_pk_bf16_f32 v7, v118, v77
	ds_write_b16 v123, v7 offset:544
	v_cvt_pk_bf16_f32 v7, v119, v77
	ds_write_b16 v123, v7 offset:816
	v_pk_mul_f32 v[112:113], v[112:113], v[82:83]
	v_pk_mul_f32 v[82:83], v[108:109], v[94:95] op_sel_hi:[0,1]
	v_cvt_pk_bf16_f32 v7, v112, v77
	ds_write_b16 v123, v7 offset:1088
	v_cvt_pk_bf16_f32 v7, v113, v77
	ds_write_b16 v123, v7 offset:1360
	v_pk_mul_f32 v[114:115], v[114:115], v[82:83]
	v_pk_mul_f32 v[82:83], v[108:109], v[106:107] op_sel_hi:[0,1]
	v_cvt_pk_bf16_f32 v7, v114, v77
	ds_write_b16 v123, v7 offset:1632
	v_cvt_pk_bf16_f32 v7, v115, v77
	ds_write_b16 v123, v7 offset:1904
	v_pk_mul_f32 v[102:103], v[102:103], v[82:83]
	v_pk_mul_f32 v[82:83], v[108:109], v[120:121] op_sel_hi:[0,1]
	v_cvt_pk_bf16_f32 v7, v102, v77
	ds_write_b16 v123, v7 offset:2176
	v_cvt_pk_bf16_f32 v7, v103, v77
	ds_write_b16 v123, v7 offset:2448
	v_pk_mul_f32 v[104:105], v[104:105], v[82:83]
	v_pk_mul_f32 v[82:83], v[108:109], v[134:135] op_sel_hi:[0,1]
	v_cvt_pk_bf16_f32 v7, v104, v77
	ds_write_b16 v123, v7 offset:2720
	v_cvt_pk_bf16_f32 v7, v105, v77
	ds_write_b16 v123, v7 offset:2992
	v_pk_mul_f32 v[98:99], v[98:99], v[82:83]
	v_pk_mul_f32 v[82:83], v[108:109], v[136:137] op_sel_hi:[0,1]
	v_cvt_pk_bf16_f32 v7, v98, v77
	ds_write_b16 v123, v7 offset:3264
	v_cvt_pk_bf16_f32 v7, v99, v77
	ds_write_b16 v123, v7 offset:3536
	v_pk_mul_f32 v[100:101], v[100:101], v[82:83]
	v_pk_mul_f32 v[82:83], v[108:109], v[138:139] op_sel_hi:[0,1]
	v_cvt_pk_bf16_f32 v7, v100, v77
	ds_write_b16 v123, v7 offset:3808
	v_cvt_pk_bf16_f32 v7, v101, v77
	ds_write_b16 v123, v7 offset:4080
	v_pk_mul_f32 v[130:131], v[130:131], v[82:83]
	v_pk_mul_f32 v[22:23], v[108:109], v[22:23] op_sel_hi:[0,1]
	v_cvt_pk_bf16_f32 v7, v130, v77
	ds_write_b16 v123, v7 offset:4352
	v_cvt_pk_bf16_f32 v7, v131, v77
	ds_write_b16 v123, v7 offset:4624
	v_pk_mul_f32 v[132:133], v[132:133], v[22:23]
	v_pk_mul_f32 v[22:23], v[108:109], v[140:141] op_sel_hi:[0,1]
	v_cvt_pk_bf16_f32 v7, v132, v77
	ds_write_b16 v123, v7 offset:4896
	v_cvt_pk_bf16_f32 v7, v133, v77
	ds_write_b16 v123, v7 offset:5168
	v_pk_mul_f32 v[126:127], v[126:127], v[22:23]
	v_pk_mul_f32 v[22:23], v[108:109], v[144:145] op_sel_hi:[0,1]
	v_cvt_pk_bf16_f32 v7, v126, v77
	ds_write_b16 v123, v7 offset:5440
	v_cvt_pk_bf16_f32 v7, v127, v77
	ds_write_b16 v123, v7 offset:5712
	v_pk_mul_f32 v[128:129], v[128:129], v[22:23]
	v_pk_mul_f32 v[22:23], v[108:109], v[146:147] op_sel_hi:[0,1]
	v_cvt_pk_bf16_f32 v7, v128, v77
	ds_write_b16 v123, v7 offset:5984
	v_cvt_pk_bf16_f32 v7, v129, v77
	ds_write_b16 v123, v7 offset:6256
	v_pk_mul_f32 v[18:19], v[18:19], v[22:23]
	v_pk_mul_f32 v[22:23], v[108:109], v[150:151] op_sel_hi:[0,1]
	v_cvt_pk_bf16_f32 v7, v18, v77
	ds_write_b16 v123, v7 offset:6528
	v_cvt_pk_bf16_f32 v7, v19, v77
	ds_write_b16 v123, v7 offset:6800
	v_pk_mul_f32 v[20:21], v[20:21], v[22:23]
	v_pk_mul_f32 v[12:13], v[108:109], v[12:13] op_sel_hi:[0,1]
	v_cvt_pk_bf16_f32 v7, v20, v77
	ds_write_b16 v123, v7 offset:7072
	v_cvt_pk_bf16_f32 v7, v21, v77
	ds_write_b16 v123, v7 offset:7344
	v_pk_mul_f32 v[12:13], v[14:15], v[12:13] op_sel:[0,1] op_sel_hi:[1,0]
	v_pk_mul_f32 v[10:11], v[108:109], v[10:11] op_sel_hi:[0,1]
	v_cvt_pk_bf16_f32 v7, v12, v77
	ds_write_b16 v123, v7 offset:7616
	v_cvt_pk_bf16_f32 v7, v13, v77
	ds_write_b16 v123, v7 offset:7888
	v_pk_mul_f32 v[14:15], v[16:17], v[10:11] op_sel:[0,1] op_sel_hi:[1,0]
	v_ashrrev_i32_e32 v9, 31, v8
	v_cvt_pk_bf16_f32 v7, v14, v77
	ds_write_b16 v123, v7 offset:8160
	v_cvt_pk_bf16_f32 v7, v15, v77
	ds_write_b16 v123, v7 offset:8432
	s_load_dwordx2 s[0:1], s[0:1], 0x108
	v_lshlrev_b64 v[82:83], 11, v[8:9]
	v_or_b32_e32 v7, s10, v152
	v_mul_lo_u32 v7, v7, s3
	v_add3_u32 v122, 0, v6, v7
	s_waitcnt lgkmcnt(0)
	v_lshl_add_u64 v[8:9], s[0:1], 0, v[82:83]
	v_lshl_add_u64 v[8:9], v[8:9], 0, v[76:77]
	s_mov_b64 s[0:1], 0x80a8000
	v_lshl_add_u64 v[10:11], v[8:9], 0, s[0:1]
	v_add_co_u32_e32 v8, vcc, s16, v8
	s_waitcnt vmcnt(0)
	v_lshlrev_b32_e32 v148, 16, v52
	v_addc_co_u32_e32 v9, vcc, 0, v9, vcc
	global_store_dwordx4 v[8:9], v[116:119], off
	global_store_dwordx4 v[10:11], v[112:115], off offset:16
	global_store_dwordx4 v[10:11], v[102:105], off offset:32
	global_store_dwordx4 v[10:11], v[98:101], off offset:48
	global_store_dwordx4 v[10:11], v[130:133], off offset:64
	global_store_dwordx4 v[10:11], v[126:129], off offset:80
	global_store_dwordx4 v[10:11], v[18:21], off offset:96
	global_store_dwordx4 v[10:11], v[12:15], off offset:112
	s_barrier
; __device__ __forceinline__ float bf_lo(unsigned w) { return __uint_as_float(w << 16); }
; __device__ __forceinline__ float bf_hi(unsigned w) { return __uint_as_float(w & 0xffff0000u); }
; #define LAS __attribute__((address_space(3)))
; __device__ __forceinline__ unsigned cvt_pk_nv(float lo, float hi) { unsigned r; asm("v_cvt_pk_bf16_f32 %0, %1, %2" : "=v"(r) : "v"(lo), "v"(hi)); return r; }
; __device__ __forceinline__ void gmlp_tile(const Ctx& C, int T, LAS unsigned char* lds, int wave, int lane, int tid) {
;     ...
; #pragma unroll
;         for (int dbi = 0; dbi < 2; ++dbi) {
;             const int db = 2 * dh + dbi;
;             v16f acc;
; #pragma unroll
;             for (int r = 0; r < 16; ++r) acc[r] = 0.f;
; #pragma unroll
;             for (int ks = 0; ks < 8; ++ks) {
;                 const bfx8 va = *(const LAS bfx8*)(VT + (32 * db + tl) * VT_STRIDE + 16 * ks + 8 * hh);
;                 acc = __builtin_amdgcn_mfma_f32_32x32x16_bf16(va, wf[ks], acc, 0, 0, 0);
;             }
; #pragma unroll
;             for (int rg = 0; rg < 4; ++rg) {
;                 const v2u u2 = uw[dbi][rg];
;                 const float o0 = bf_lo(u2.x) * (acc[4 * rg + 0] + bias), o1 = bf_hi(u2.x) * (acc[4 * rg + 1] + bias);
;                 const float o2 = bf_lo(u2.y) * (acc[4 * rg + 2] + bias), o3 = bf_hi(u2.y) * (acc[4 * rg + 3] + bias);
;                 ssq += (o0 * o0 + o1 * o1) + (o2 * o2 + o3 * o3);
;                 outp[h][dbi][2 * rg] = cvt_pk_nv(o0, o1); outp[h][dbi][2 * rg + 1] = cvt_pk_nv(o2, o3);
;             }
;         }
	ds_read_b128 v[6:9], v122
	ds_read_b128 v[98:101], v122 offset:32
	s_waitcnt lgkmcnt(1)
	v_mfma_f32_32x32x16_bf16 v[8:23], v[6:9], v[0:3], 0
	v_lshlrev_b32_e32 v6, 16, v74
	v_and_b32_e32 v149, 0xffff0000, v52
	s_mov_b32 s0, 0x2928000
	v_lshlrev_b32_e32 v150, 16, v53
	v_and_b32_e32 v151, 0xffff0000, v53
	v_lshlrev_b32_e32 v113, 2, v153
	v_lshlrev_b32_e32 v152, 16, v54
	s_waitcnt lgkmcnt(0)
	v_mfma_f32_32x32x16_bf16 v[8:23], v[98:101], v[64:67], v[8:23]
	ds_read_b128 v[98:101], v122 offset:64
	ds_read_b128 v[102:105], v122 offset:96
	v_and_b32_e32 v153, 0xffff0000, v54
	v_lshlrev_b32_e32 v154, 16, v55
	v_and_b32_e32 v155, 0xffff0000, v55
	v_pk_mul_f32 v[52:53], v[154:155], v[154:155]
	v_lshlrev_b32_e32 v156, 16, v36
	v_and_b32_e32 v157, 0xffff0000, v36
	s_waitcnt lgkmcnt(1)
	v_mfma_f32_32x32x16_bf16 v[8:23], v[98:101], v[60:63], v[8:23]
	v_mul_f32_e64 v54, v156, v156
	v_mul_f32_e64 v55, v157, v157
	v_lshlrev_b32_e32 v158, 16, v37
	v_and_b32_e32 v159, 0xffff0000, v37
	v_mul_f32_e64 v36, v158, v158
	v_mul_f32_e64 v37, v159, v159
	v_and_b32_e32 v108, 63, v160
	v_lshlrev_b32_e32 v160, 16, v38
	v_and_b32_e32 v161, 0xffff0000, v38
	s_waitcnt lgkmcnt(0)
	v_mfma_f32_32x32x16_bf16 v[8:23], v[102:105], v[56:59], v[8:23]
	ds_read_b128 v[98:101], v122 offset:128
	ds_read_b128 v[102:105], v122 offset:160
	v_mul_f32_e64 v162, v160, v160
	v_mul_f32_e64 v163, v161, v161
	v_lshlrev_b32_e32 v164, 16, v39
	v_and_b32_e32 v165, 0xffff0000, v39
	v_pk_mul_f32 v[38:39], v[164:165], v[164:165]
	v_pk_mul_f32 v[168:169], v[166:167], v[166:167]
	v_lshlrev_b32_e32 v170, 16, v29
	s_waitcnt lgkmcnt(1)
	v_mfma_f32_32x32x16_bf16 v[8:23], v[98:101], v[48:51], v[8:23]
	v_and_b32_e32 v171, 0xffff0000, v29
	v_mul_f32_e64 v28, v170, v170
	v_mul_f32_e64 v29, v171, v171
	v_lshlrev_b32_e32 v172, 16, v30
	v_and_b32_e32 v173, 0xffff0000, v30
	v_pk_mul_f32 v[174:175], v[172:173], v[172:173]
	v_lshlrev_b32_e32 v176, 16, v31
	v_and_b32_e32 v177, 0xffff0000, v31
	s_waitcnt lgkmcnt(0)
	v_mfma_f32_32x32x16_bf16 v[8:23], v[102:105], v[44:47], v[8:23]
	ds_read_b128 v[98:101], v122 offset:192
	ds_read_b128 v[102:105], v122 offset:224
	v_mul_f32_e64 v30, v176, v176
	v_mul_f32_e64 v31, v177, v177
	v_and_b32_e32 v179, 0xffff0000, v24
	v_pk_mul_f32 v[180:181], v[178:179], v[178:179]
	v_lshlrev_b32_e32 v190, 16, v25
	v_and_b32_e32 v191, 0xffff0000, v25
	v_pk_mul_f32 v[24:25], v[190:191], v[190:191]
	s_waitcnt lgkmcnt(1)
	v_mfma_f32_32x32x16_bf16 v[8:23], v[98:101], v[40:43], v[8:23]
	ds_read_b128 v[98:101], v122 offset:8736
	s_waitcnt lgkmcnt(1)
	v_mfma_f32_32x32x16_bf16 v[8:23], v[102:105], v[32:35], v[8:23]
	ds_read_b128 v[102:105], v122 offset:8768
	s_nop 10
	v_add_f32_e32 v7, v125, v8
	v_mul_f32_e32 v6, v7, v6
	v_and_b32_e32 v7, 0xffff0000, v74
	v_add_f32_e32 v8, v125, v9
	v_mul_f32_e32 v7, v8, v7
	v_lshlrev_b32_e32 v8, 16, v75
	v_add_f32_e32 v9, v125, v10
	v_mul_f32_e32 v8, v9, v8
	v_and_b32_e32 v9, 0xffff0000, v75
	v_add_f32_e32 v10, v125, v11
	v_mul_f32_e32 v9, v10, v9
	v_mul_f32_e32 v10, v7, v7
	v_fmac_f32_e32 v10, v6, v6
	v_cvt_pk_bf16_f32 v112, v6, v7
	v_lshlrev_b32_e32 v6, 16, v4
	v_add_f32_e32 v7, v125, v12
	v_mul_f32_e32 v75, v7, v6
	v_and_b32_e32 v4, 0xffff0000, v4
	v_add_f32_e32 v6, v125, v13
	v_mul_f32_e32 v11, v9, v9
	v_mul_f32_e32 v86, v6, v4
	v_lshlrev_b32_e32 v4, 16, v5
	v_add_f32_e32 v6, v125, v14
	v_fmac_f32_e32 v11, v8, v8
	v_cvt_pk_bf16_f32 v111, v8, v9
	v_mul_f32_e32 v87, v6, v4
	v_and_b32_e32 v8, 0xffff0000, v5
	ds_read_b128 v[4:7], v122 offset:8704
	v_add_f32_e32 v9, v125, v15
	v_mul_f32_e32 v90, v9, v8
	v_mul_f32_e32 v8, v86, v86
	v_mul_f32_e32 v9, v90, v90
	v_fmac_f32_e32 v8, v75, v75
	v_fmac_f32_e32 v9, v87, v87
	v_add_f32_e32 v74, v10, v11
	v_add_f32_e32 v91, v8, v9
	s_waitcnt lgkmcnt(0)
	v_mfma_f32_32x32x16_bf16 v[0:15], v[4:7], v[0:3], 0
	v_cvt_pk_bf16_f32 v115, v75, v86
	v_lshlrev_b32_e32 v75, 16, v72
	v_add_f32_e32 v16, v125, v16
	v_mul_f32_e32 v75, v16, v75
	v_and_b32_e32 v16, 0xffff0000, v72
	v_add_f32_e32 v17, v125, v17
	v_mul_f32_e32 v72, v17, v16
	v_mfma_f32_32x32x16_bf16 v[0:15], v[98:101], v[64:67], v[0:15]
	ds_read_b128 v[64:67], v122 offset:8800
	v_lshlrev_b32_e32 v16, 16, v73
	v_add_f32_e32 v17, v125, v18
	v_mul_f32_e32 v86, v17, v16
	v_and_b32_e32 v16, 0xffff0000, v73
	v_add_f32_e32 v17, v125, v19
	v_add_f32_e32 v74, v74, v91
	v_mfma_f32_32x32x16_bf16 v[0:15], v[102:105], v[60:63], v[0:15]
	v_mul_f32_e32 v60, v17, v16
	ds_read_b128 v[16:19], v122 offset:8832
	v_mul_f32_e32 v61, v72, v72
	v_mul_f32_e32 v62, v60, v60
	v_fmac_f32_e32 v61, v75, v75
	v_fmac_f32_e32 v62, v86, v86
	v_cvt_pk_bf16_f32 v116, v86, v60
	s_waitcnt lgkmcnt(1)
	v_mfma_f32_32x32x16_bf16 v[0:15], v[64:67], v[56:59], v[0:15]
	v_add_f32_e32 v56, v61, v62
	v_add_f32_e32 v61, v56, v74
	ds_read_b128 v[56:59], v122 offset:8864
	v_lshlrev_b32_e32 v60, 16, v70
	v_cvt_pk_bf16_f32 v114, v87, v90
	v_cvt_pk_bf16_f32 v117, v75, v72
	s_waitcnt lgkmcnt(1)
	v_mfma_f32_32x32x16_bf16 v[0:15], v[16:19], v[48:51], v[0:15]
	v_add_f32_e32 v16, v125, v20
	v_mul_f32_e32 v48, v16, v60
	v_and_b32_e32 v16, 0xffff0000, v70
	v_add_f32_e32 v17, v125, v21
	v_mul_f32_e32 v49, v17, v16
	ds_read_b128 v[16:19], v122 offset:8896
	v_lshlrev_b32_e32 v20, 16, v71
	s_waitcnt lgkmcnt(1)
	v_mfma_f32_32x32x16_bf16 v[0:15], v[56:59], v[44:47], v[0:15]
	v_add_f32_e32 v21, v125, v22
	v_mul_f32_e32 v44, v21, v20
	v_and_b32_e32 v20, 0xffff0000, v71
	v_add_f32_e32 v21, v125, v23
	v_mul_f32_e32 v45, v21, v20
	ds_read_b128 v[20:23], v122 offset:8928
	v_mul_f32_e32 v46, v49, v49
	s_waitcnt lgkmcnt(1)
; __device__ __forceinline__ float bf_lo(unsigned w) { return __uint_as_float(w << 16); }
; __device__ __forceinline__ float bf_hi(unsigned w) { return __uint_as_float(w & 0xffff0000u); }
;     __device__ __forceinline__ const float* in(int i) const { return karg_in(i); }
; __device__ __forceinline__ void gmlp_tile(const Ctx& C, int T, LAS unsigned char* lds, int wave, int lane, int tid) {
;     ...
;     for (int h = 0; h < 4; ++h) {
;         bfx8 wf[8];
;         const bf16* wrow = Weff + ((size_t)(mode * 4 + h) * 128 + t) * 128 + 8 * hh;
; #pragma unroll
;         for (int ks = 0; ks < 8; ++ks) wf[ks] = *(const bfx8*)(wrow + 16 * ks);
;         v2u uw[2][4];
; #pragma unroll
;         for (int dbi = 0; dbi < 2; ++dbi)
; #pragma unroll
;             for (int rg = 0; rg < 4; ++rg) uw[dbi][rg] = *(const v2u*)(zt + h * 128 + 32 * (2 * dh + dbi) + 8 * rg + 4 * hh);
;         const float bias = C.in(13)[h * 128 + (mode ? (t & 15) : t)];
;         v4f gvv[8];
;         { const float* gvp = C.in(11) + h * 128 + q * 32;
; #pragma unroll
;           for (int i = 0; i < 8; ++i) gvv[i] = *(const v4f*)(gvp + 4 * i); }
;         __syncthreads();
;         {
;             float v[32]; float s = 0.f;
; #pragma unroll
;             for (int i = 0; i < 4; ++i) { const v4u w = vraw[i];
;                 v[8 * i + 0] = bf_lo(w.x); v[8 * i + 1] = bf_hi(w.x); v[8 * i + 2] = bf_lo(w.y); v[8 * i + 3] = bf_hi(w.y);
;                 v[8 * i + 4] = bf_lo(w.z); v[8 * i + 5] = bf_hi(w.z); v[8 * i + 6] = bf_lo(w.w); v[8 * i + 7] = bf_hi(w.w); }
;             if (h < 3) {
; #pragma unroll
;                 for (int i = 0; i < 4; ++i) vraw[i] = *(const v4u*)(vsrc + (h + 1) * 128 + 8 * i);
;             }
; #pragma unroll
;             for (int i = 0; i < 32; ++i) s += v[i] * v[i];
;             s += __shfl_xor(s, 1); s += __shfl_xor(s, 2);
;     ...
;             for (int rg = 0; rg < 4; ++rg) {
;                 const v2u u2 = uw[dbi][rg];
;                 const float o0 = bf_lo(u2.x) * (acc[4 * rg + 0] + bias), o1 = bf_hi(u2.x) * (acc[4 * rg + 1] + bias);
;                 const float o2 = bf_lo(u2.y) * (acc[4 * rg + 2] + bias), o3 = bf_hi(u2.y) * (acc[4 * rg + 3] + bias);
;                 ssq += (o0 * o0 + o1 * o1) + (o2 * o2 + o3 * o3);
;                 outp[h][dbi][2 * rg] = cvt_pk_nv(o0, o1); outp[h][dbi][2 * rg + 1] = cvt_pk_nv(o2, o3);
;             }
;         }
	v_mfma_f32_32x32x16_bf16 v[0:15], v[16:19], v[40:43], v[0:15]
	v_mul_f32_e32 v16, v45, v45
	v_fmac_f32_e32 v46, v48, v48
	v_fmac_f32_e32 v16, v44, v44
	v_add_f32_e32 v16, v46, v16
	v_add_f32_e32 v18, v16, v61
	v_lshlrev_b32_e32 v16, 16, v68
	v_pk_mul_f32 v[40:41], v[150:151], v[150:151]
	s_waitcnt lgkmcnt(0)
	v_mfma_f32_32x32x16_bf16 v[0:15], v[20:23], v[32:35], v[0:15]
	v_mul_f32_e64 v34, v148, v148
	v_mul_f32_e64 v35, v149, v149
	v_cvt_pk_bf16_f32 v121, v48, v49
	v_cvt_pk_bf16_f32 v119, v44, v45
	v_mul_f32_e64 v42, v152, v152
	v_mul_f32_e64 v43, v153, v153
	v_add_f32_e32 v34, v34, v35
	v_add_f32_e32 v34, v40, v34
	v_add_f32_e32 v34, v41, v34
	s_nop 4
	v_add_f32_e32 v0, v125, v0
	v_mul_f32_e32 v19, v0, v16
	v_and_b32_e32 v0, 0xffff0000, v68
	v_add_f32_e32 v1, v125, v1
	v_mul_f32_e32 v20, v1, v0
	v_lshlrev_b32_e32 v0, 16, v69
	v_add_f32_e32 v1, v125, v2
	v_add_co_u32_e32 v16, vcc, s0, v78
	v_mul_f32_e32 v21, v1, v0
	v_and_b32_e32 v0, 0xffff0000, v69
	v_add_f32_e32 v1, v125, v3
	v_addc_co_u32_e32 v17, vcc, 0, v79, vcc
	s_mov_b64 s[0:1], s[80:81]
	v_mul_f32_e32 v22, v1, v0
	global_load_dwordx4 v[0:3], v[16:17], off offset:-3584
	global_load_dwordx4 v[72:75], v[16:17], off offset:-2560
	global_load_dwordx4 v[68:71], v[16:17], off offset:-1536
	global_load_dwordx4 v[64:67], v[16:17], off offset:-512
	global_load_dwordx4 v[60:63], v[16:17], off offset:512
	global_load_dwordx4 v[56:59], v[16:17], off offset:1536
	global_load_dwordx4 v[48:51], v[16:17], off offset:2560
	global_load_dwordx4 v[44:47], v[16:17], off offset:3584
	global_load_dwordx2 v[106:107], v[80:81], off offset:256
	global_load_dwordx2 v[104:105], v[80:81], off offset:272
	global_load_dwordx2 v[102:103], v[80:81], off offset:288
	global_load_dwordx2 v[100:101], v[80:81], off offset:304
	global_load_dwordx2 v[98:99], v[80:81], off offset:320
	global_load_dwordx2 v[94:95], v[80:81], off offset:336
	global_load_dwordx2 v[90:91], v[80:81], off offset:352
	global_load_dwordx2 v[86:87], v[80:81], off offset:368
	s_load_dwordx2 s[0:1], s[0:1], 0x68
	v_add_f32_e32 v34, v42, v34
	v_add_f32_e32 v34, v43, v34
	v_add_f32_e32 v34, v52, v34
	v_add_f32_e32 v34, v53, v34
	v_add_f32_e32 v34, v54, v34
	s_waitcnt lgkmcnt(0)
	global_load_dword v143, v124, s[0:1] offset:512
	s_mov_b64 s[0:1], s[80:81]
	v_add_f32_e32 v34, v55, v34
	s_load_dwordx2 s[12:13], s[0:1], 0x58
	v_add_f32_e32 v34, v36, v34
	v_add_f32_e32 v34, v37, v34
	v_add_f32_e32 v34, v162, v34
	v_mul_f32_e32 v23, v20, v20
	v_mul_f32_e32 v16, v22, v22
	v_add_f32_e32 v34, v163, v34
	v_fmac_f32_e32 v23, v19, v19
	v_fmac_f32_e32 v16, v21, v21
	v_add_f32_e32 v34, v38, v34
	v_add_f32_e32 v16, v23, v16
	v_cvt_pk_bf16_f32 v120, v19, v20
	v_cvt_pk_bf16_f32 v118, v21, v22
	s_waitcnt lgkmcnt(0)
	global_load_dwordx4 v[20:23], v76, s[12:13] offset:560
	global_load_dwordx4 v[126:129], v76, s[12:13] offset:544
	global_load_dwordx4 v[130:133], v76, s[12:13] offset:528
	global_load_dwordx4 v[134:137], v76, s[12:13] offset:512
	global_load_dwordx4 v[138:141], v76, s[12:13] offset:592
	global_load_dwordx4 v[144:147], v76, s[12:13] offset:576
	v_add_f32_e32 v34, v39, v34
	v_add_f32_e32 v34, v168, v34
	v_add_f32_e32 v34, v169, v34
	v_add_f32_e32 v28, v28, v34
	v_add_f32_e32 v28, v29, v28
	v_add_f32_e32 v28, v174, v28
	v_add_f32_e32 v28, v175, v28
	v_add_f32_e32 v28, v30, v28
	v_add_f32_e32 v28, v31, v28
	v_add_f32_e32 v28, v180, v28
	v_add_f32_e32 v28, v181, v28
	v_add_f32_e32 v142, v18, v16
	v_and_b32_e32 v18, 0xffff0000, v26
	v_lshlrev_b32_e32 v19, 16, v26
	v_add_f32_e32 v24, v24, v28
	v_pk_mul_f32 v[32:33], v[18:19], v[18:19]
	v_add_f32_e32 v24, v25, v24
	v_and_b32_e32 v16, 0xffff0000, v27
	v_lshlrev_b32_e32 v17, 16, v27
	v_add_f32_e32 v24, v33, v24
	v_pk_mul_f32 v[26:27], v[16:17], v[16:17]
	v_add_f32_e32 v24, v32, v24
	v_add_f32_e32 v24, v27, v24
	v_add_f32_e32 v24, v26, v24
	ds_bpermute_b32 v25, v183, v24
	v_add_f32_e32 v4, v125, v4
	v_mul_f32_e32 v162, v4, v189
	v_and_b32_e32 v4, 0xffff0000, v96
	v_add_f32_e32 v5, v125, v5
	v_mul_f32_e32 v96, v5, v4
	s_waitcnt lgkmcnt(0)
	v_add_f32_e32 v4, v24, v25
	global_load_dwordx4 v[24:27], v76, s[12:13] offset:624
	global_load_dwordx4 v[28:31], v76, s[12:13] offset:608
	ds_bpermute_b32 v5, v184, v4
	s_waitcnt lgkmcnt(0)
	s_barrier
; __device__ __forceinline__ float bf_lo(unsigned w) { return __uint_as_float(w << 16); }
; __device__ __forceinline__ float bf_hi(unsigned w) { return __uint_as_float(w & 0xffff0000u); }
; __device__ __forceinline__ bf16 f2bf(float f) { return (bf16)(cvt_pk_nv(f, 0.f) & 0xffffu); }
;     __device__ __forceinline__ float* out() const { return (float*)karg_in(33); }
; __device__ __forceinline__ void gmlp_tile(const Ctx& C, int T, LAS unsigned char* lds, int wave, int lane, int tid) {
;     ...
;         __syncthreads();
;         {
;             float v[32]; float s = 0.f;
; #pragma unroll
;             for (int i = 0; i < 4; ++i) { const v4u w = vraw[i];
;                 v[8 * i + 0] = bf_lo(w.x); v[8 * i + 1] = bf_hi(w.x); v[8 * i + 2] = bf_lo(w.y); v[8 * i + 3] = bf_hi(w.y);
;                 v[8 * i + 4] = bf_lo(w.z); v[8 * i + 5] = bf_hi(w.z); v[8 * i + 6] = bf_lo(w.w); v[8 * i + 7] = bf_hi(w.w); }
;             if (h < 3) {
; #pragma unroll
;                 for (int i = 0; i < 4; ++i) vraw[i] = *(const v4u*)(vsrc + (h + 1) * 128 + 8 * i);
;             }
; #pragma unroll
;             for (int i = 0; i < 32; ++i) s += v[i] * v[i];
;             s += __shfl_xor(s, 1); s += __shfl_xor(s, 2);
;             const float r = rsqrtf(s * (1.f / 128.f) + EPS);
; #pragma unroll
;             for (int i = 0; i < 32; ++i) { v[i] = v[i] * r * gvv[i >> 2][i & 3]; VT[(q * 32 + i) * VT_STRIDE + row] = f2bf(v[i]); }
;             if (mode) { float* ov = C.out() + OFF_V_S + (size_t)row * AW + h * 128 + q * 32;
; #pragma unroll
;                 for (int i = 0; i < 8; ++i) *(v4f*)(ov + 4 * i) = (v4f){v[4 * i], v[4 * i + 1], v[4 * i + 2], v[4 * i + 3]}; }
;         }
;         __syncthreads();
	global_load_dwordx4 v[32:35], v[84:85], off offset:560
	global_load_dwordx4 v[36:39], v[84:85], off offset:544
	global_load_dwordx4 v[40:43], v[84:85], off offset:528
	global_load_dwordx4 v[52:55], v[84:85], off offset:512
	v_add_f32_e32 v4, v4, v5
	v_fmamk_f32 v4, v4, 0x3c000000, v110
	v_mul_f32_e32 v5, 0x4b800000, v4
	v_cmp_gt_f32_e32 vcc, s11, v4
	s_mov_b64 s[0:1], s[80:81]
	v_add_f32_e32 v8, v125, v8
	v_cndmask_b32_e32 v4, v4, v5, vcc
	v_rsq_f32_e32 v4, v4
	s_waitcnt vmcnt(3)
	v_lshlrev_b32_e32 v204, 16, v32
	v_mul_f32_e32 v5, 0x45800000, v4
	v_cndmask_b32_e32 v4, v4, v5, vcc
	v_pk_mul_f32 v[148:149], v[4:5], v[148:149] op_sel_hi:[0,1]
	v_pk_mul_f32 v[134:135], v[134:135], v[148:149]
	s_waitcnt vmcnt(0)
	v_lshlrev_b32_e32 v168, 16, v52
	v_cvt_pk_bf16_f32 v5, v134, v77
	ds_write_b16 v123, v5
	v_cvt_pk_bf16_f32 v5, v135, v77
	ds_write_b16 v123, v5 offset:272
	v_pk_mul_f32 v[148:149], v[4:5], v[150:151] op_sel_hi:[0,1]
	v_pk_mul_f32 v[136:137], v[136:137], v[148:149]
	v_and_b32_e32 v169, 0xffff0000, v52
	v_cvt_pk_bf16_f32 v5, v136, v77
	ds_write_b16 v123, v5 offset:544
	v_cvt_pk_bf16_f32 v5, v137, v77
	ds_write_b16 v123, v5 offset:816
	v_pk_mul_f32 v[148:149], v[4:5], v[152:153] op_sel_hi:[0,1]
	v_pk_mul_f32 v[130:131], v[130:131], v[148:149]
	v_lshlrev_b32_e32 v174, 16, v55
	v_cvt_pk_bf16_f32 v5, v130, v77
	ds_write_b16 v123, v5 offset:1088
	v_cvt_pk_bf16_f32 v5, v131, v77
	ds_write_b16 v123, v5 offset:1360
	v_pk_mul_f32 v[148:149], v[4:5], v[154:155] op_sel_hi:[0,1]
	v_pk_mul_f32 v[132:133], v[132:133], v[148:149]
	v_and_b32_e32 v175, 0xffff0000, v55
	v_cvt_pk_bf16_f32 v5, v132, v77
	ds_write_b16 v123, v5 offset:1632
	v_cvt_pk_bf16_f32 v5, v133, v77
	ds_write_b16 v123, v5 offset:1904
	v_pk_mul_f32 v[148:149], v[4:5], v[156:157] op_sel_hi:[0,1]
	v_pk_mul_f32 v[126:127], v[126:127], v[148:149]
	v_lshlrev_b32_e32 v180, 16, v42
	v_cvt_pk_bf16_f32 v5, v126, v77
	ds_write_b16 v123, v5 offset:2176
	v_cvt_pk_bf16_f32 v5, v127, v77
	ds_write_b16 v123, v5 offset:2448
	v_pk_mul_f32 v[148:149], v[4:5], v[158:159] op_sel_hi:[0,1]
	v_pk_mul_f32 v[128:129], v[128:129], v[148:149]
	v_and_b32_e32 v181, 0xffff0000, v42
	v_cvt_pk_bf16_f32 v5, v128, v77
	ds_write_b16 v123, v5 offset:2720
	v_cvt_pk_bf16_f32 v5, v129, v77
	ds_write_b16 v123, v5 offset:2992
	v_pk_mul_f32 v[148:149], v[4:5], v[160:161] op_sel_hi:[0,1]
	v_pk_mul_f32 v[20:21], v[20:21], v[148:149]
	v_pk_mul_f32 v[160:161], v[168:169], v[168:169]
	v_cvt_pk_bf16_f32 v5, v20, v77
	ds_write_b16 v123, v5 offset:3264
	v_cvt_pk_bf16_f32 v5, v21, v77
	ds_write_b16 v123, v5 offset:3536
	v_pk_mul_f32 v[148:149], v[4:5], v[164:165] op_sel_hi:[0,1]
	v_pk_mul_f32 v[22:23], v[22:23], v[148:149]
	v_add_f32_e32 v150, v160, v161
	v_cvt_pk_bf16_f32 v5, v22, v77
	ds_write_b16 v123, v5 offset:3808
	v_cvt_pk_bf16_f32 v5, v23, v77
	ds_write_b16 v123, v5 offset:4080
	v_pk_mul_f32 v[148:149], v[4:5], v[166:167] op_sel_hi:[0,1]
	v_pk_mul_f32 v[144:145], v[144:145], v[148:149]
	v_pk_mul_f32 v[166:167], v[180:181], v[180:181]
	v_cvt_pk_bf16_f32 v5, v144, v77
	ds_write_b16 v123, v5 offset:4352
	v_cvt_pk_bf16_f32 v5, v145, v77
	ds_write_b16 v123, v5 offset:4624
	v_pk_mul_f32 v[148:149], v[4:5], v[170:171] op_sel_hi:[0,1]
	v_pk_mul_f32 v[146:147], v[146:147], v[148:149]
	v_lshlrev_b32_e32 v170, 16, v53
	v_cvt_pk_bf16_f32 v5, v146, v77
	ds_write_b16 v123, v5 offset:4896
	v_cvt_pk_bf16_f32 v5, v147, v77
	ds_write_b16 v123, v5 offset:5168
	v_pk_mul_f32 v[148:149], v[4:5], v[172:173] op_sel_hi:[0,1]
	v_pk_mul_f32 v[138:139], v[138:139], v[148:149]
	v_and_b32_e32 v171, 0xffff0000, v53
	v_cvt_pk_bf16_f32 v5, v138, v77
	ds_write_b16 v123, v5 offset:5440
	v_cvt_pk_bf16_f32 v5, v139, v77
	ds_write_b16 v123, v5 offset:5712
	v_pk_mul_f32 v[148:149], v[4:5], v[176:177] op_sel_hi:[0,1]
	v_pk_mul_f32 v[140:141], v[140:141], v[148:149]
	v_pk_mul_f32 v[52:53], v[170:171], v[170:171]
	v_cvt_pk_bf16_f32 v5, v140, v77
	ds_write_b16 v123, v5 offset:5984
	v_cvt_pk_bf16_f32 v5, v141, v77
	ds_write_b16 v123, v5 offset:6256
	v_pk_mul_f32 v[148:149], v[4:5], v[178:179] op_sel_hi:[0,1]
	v_pk_mul_f32 v[28:29], v[28:29], v[148:149]
	v_lshlrev_b32_e32 v172, 16, v54
	v_cvt_pk_bf16_f32 v5, v28, v77
	ds_write_b16 v123, v5 offset:6528
	v_cvt_pk_bf16_f32 v5, v29, v77
	ds_write_b16 v123, v5 offset:6800
	v_pk_mul_f32 v[148:149], v[4:5], v[190:191] op_sel_hi:[0,1]
	v_pk_mul_f32 v[30:31], v[30:31], v[148:149]
	v_and_b32_e32 v173, 0xffff0000, v54
	v_cvt_pk_bf16_f32 v5, v30, v77
	ds_write_b16 v123, v5 offset:7072
	v_cvt_pk_bf16_f32 v5, v31, v77
	ds_write_b16 v123, v5 offset:7344
	v_pk_mul_f32 v[18:19], v[4:5], v[18:19] op_sel_hi:[0,1]
	v_pk_mul_f32 v[24:25], v[24:25], v[18:19] op_sel:[0,1] op_sel_hi:[1,0]
	v_add_f32_e32 v52, v52, v150
	v_cvt_pk_bf16_f32 v5, v24, v77
	ds_write_b16 v123, v5 offset:7616
	v_cvt_pk_bf16_f32 v5, v25, v77
	ds_write_b16 v123, v5 offset:7888
	v_pk_mul_f32 v[4:5], v[4:5], v[16:17] op_sel_hi:[0,1]
	v_pk_mul_f32 v[26:27], v[26:27], v[4:5] op_sel:[0,1] op_sel_hi:[1,0]
	v_add_f32_e32 v5, v125, v6
	v_cvt_pk_bf16_f32 v4, v26, v77
	ds_write_b16 v123, v4 offset:8160
	v_cvt_pk_bf16_f32 v4, v27, v77
	ds_write_b16 v123, v4 offset:8432
	s_load_dwordx2 s[0:1], s[0:1], 0x108
	v_lshlrev_b32_e32 v4, 16, v97
	v_mul_f32_e32 v148, v5, v4
	v_and_b32_e32 v6, 0xffff0000, v97
	v_add_f32_e32 v52, v53, v52
	s_waitcnt lgkmcnt(0)
	v_lshl_add_u64 v[4:5], s[0:1], 0, v[82:83]
	v_lshl_add_u64 v[4:5], v[4:5], 0, v[76:77]
	s_mov_b64 s[0:1], 0x80a8200
	v_lshl_add_u64 v[16:17], v[4:5], 0, s[0:1]
	v_add_co_u32_e32 v4, vcc, s16, v4
	s_mov_b32 s0, 0x2930000
	s_nop 0
	v_addc_co_u32_e32 v5, vcc, 0, v5, vcc
	global_store_dwordx4 v[4:5], v[134:137], off offset:512
	global_store_dwordx4 v[16:17], v[130:133], off offset:16
	global_store_dwordx4 v[16:17], v[126:129], off offset:32
	global_store_dwordx4 v[16:17], v[20:23], off offset:48
	global_store_dwordx4 v[16:17], v[144:147], off offset:64
	global_store_dwordx4 v[16:17], v[138:141], off offset:80
	global_store_dwordx4 v[16:17], v[28:31], off offset:96
	global_store_dwordx4 v[16:17], v[24:27], off offset:112
	s_barrier
; __device__ __forceinline__ float bf_lo(unsigned w) { return __uint_as_float(w << 16); }
; __device__ __forceinline__ float bf_hi(unsigned w) { return __uint_as_float(w & 0xffff0000u); }
; #define LAS __attribute__((address_space(3)))
; __device__ __forceinline__ unsigned cvt_pk_nv(float lo, float hi) { unsigned r; asm("v_cvt_pk_bf16_f32 %0, %1, %2" : "=v"(r) : "v"(lo), "v"(hi)); return r; }
; __device__ __forceinline__ void gmlp_tile(const Ctx& C, int T, LAS unsigned char* lds, int wave, int lane, int tid) {
;     ...
; #pragma unroll
;         for (int dbi = 0; dbi < 2; ++dbi) {
;             const int db = 2 * dh + dbi;
;             v16f acc;
; #pragma unroll
;             for (int r = 0; r < 16; ++r) acc[r] = 0.f;
; #pragma unroll
;             for (int ks = 0; ks < 8; ++ks) {
;                 const bfx8 va = *(const LAS bfx8*)(VT + (32 * db + tl) * VT_STRIDE + 16 * ks + 8 * hh);
;                 acc = __builtin_amdgcn_mfma_f32_32x32x16_bf16(va, wf[ks], acc, 0, 0, 0);
;             }
; #pragma unroll
;             for (int rg = 0; rg < 4; ++rg) {
;                 const v2u u2 = uw[dbi][rg];
;                 const float o0 = bf_lo(u2.x) * (acc[4 * rg + 0] + bias), o1 = bf_hi(u2.x) * (acc[4 * rg + 1] + bias);
;                 const float o2 = bf_lo(u2.y) * (acc[4 * rg + 2] + bias), o3 = bf_hi(u2.y) * (acc[4 * rg + 3] + bias);
;                 ssq += (o0 * o0 + o1 * o1) + (o2 * o2 + o3 * o3);
;                 outp[h][dbi][2 * rg] = cvt_pk_nv(o0, o1); outp[h][dbi][2 * rg + 1] = cvt_pk_nv(o2, o3);
;             }
;         }
	ds_read_b128 v[16:19], v122
	v_add_f32_e32 v4, v125, v7
	v_mul_f32_e32 v97, v4, v6
	v_mul_f32_e32 v4, v96, v96
	v_mul_f32_e32 v5, v97, v97
	v_fmac_f32_e32 v4, v162, v162
	v_fmac_f32_e32 v5, v148, v148
	v_add_f32_e32 v126, v4, v5
	ds_read_b128 v[4:7], v122 offset:32
	s_waitcnt lgkmcnt(1)
	v_mfma_f32_32x32x16_bf16 v[16:31], v[16:19], v[0:3], 0
	ds_read_b128 v[132:135], v122 offset:64
	v_cvt_pk_bf16_f32 v130, v162, v96
	v_lshlrev_b32_e32 v96, 16, v92
	v_cvt_pk_bf16_f32 v127, v148, v97
	v_mul_f32_e32 v96, v8, v96
	v_and_b32_e32 v8, 0xffff0000, v93
	v_add_f32_e32 v126, v126, v142
	s_waitcnt lgkmcnt(1)
	v_mfma_f32_32x32x16_bf16 v[16:31], v[4:7], v[72:75], v[16:31]
	v_and_b32_e32 v4, 0xffff0000, v92
	v_add_f32_e32 v5, v125, v9
	v_mul_f32_e32 v92, v5, v4
	v_lshlrev_b32_e32 v4, 16, v93
	v_add_f32_e32 v5, v125, v10
	v_mul_f32_e32 v97, v5, v4
	ds_read_b128 v[4:7], v122 offset:96
	s_waitcnt lgkmcnt(1)
	v_mfma_f32_32x32x16_bf16 v[16:31], v[132:135], v[68:71], v[16:31]
	v_add_f32_e32 v9, v125, v11
	v_mul_f32_e32 v93, v9, v8
	ds_read_b128 v[8:11], v122 offset:128
	v_mul_f32_e32 v128, v92, v92
	v_mul_f32_e32 v129, v93, v93
	v_fmac_f32_e32 v128, v96, v96
	v_fmac_f32_e32 v129, v97, v97
	s_waitcnt lgkmcnt(1)
	v_mfma_f32_32x32x16_bf16 v[16:31], v[4:7], v[64:67], v[16:31]
	v_add_f32_e32 v4, v128, v129
	v_add_f32_e32 v126, v4, v126
	ds_read_b128 v[4:7], v122 offset:160
	v_cvt_pk_bf16_f32 v131, v96, v92
	v_lshlrev_b32_e32 v92, 16, v88
	v_cvt_pk_bf16_f32 v128, v97, v93
	v_mul_f32_e64 v162, v172, v172
	v_mul_f32_e64 v163, v173, v173
	s_waitcnt lgkmcnt(1)
	v_mfma_f32_32x32x16_bf16 v[16:31], v[8:11], v[60:63], v[16:31]
	v_add_f32_e32 v8, v125, v12
	v_mul_f32_e32 v12, v8, v92
	v_and_b32_e32 v8, 0xffff0000, v88
	v_add_f32_e32 v9, v125, v13
	v_mul_f32_e32 v13, v9, v8
	ds_read_b128 v[8:11], v122 offset:192
	v_lshlrev_b32_e32 v88, 16, v89
	s_waitcnt lgkmcnt(1)
	v_mfma_f32_32x32x16_bf16 v[16:31], v[4:7], v[56:59], v[16:31]
	v_add_f32_e32 v4, v125, v14
	v_mul_f32_e32 v14, v4, v88
	v_and_b32_e32 v4, 0xffff0000, v89
	v_add_f32_e32 v5, v125, v15
	v_mul_f32_e32 v15, v5, v4
	ds_read_b128 v[4:7], v122 offset:224
	v_mul_f32_e32 v88, v13, v13
	s_waitcnt lgkmcnt(1)
	v_mfma_f32_32x32x16_bf16 v[16:31], v[8:11], v[48:51], v[16:31]
	v_mul_f32_e32 v8, v15, v15
	v_fmac_f32_e32 v88, v12, v12
	v_fmac_f32_e32 v8, v14, v14
	v_add_f32_e32 v8, v88, v8
	v_add_f32_e32 v8, v8, v126
	v_cvt_pk_bf16_f32 v132, v12, v13
	v_cvt_pk_bf16_f32 v129, v14, v15
	s_waitcnt lgkmcnt(0)
	v_mfma_f32_32x32x16_bf16 v[16:31], v[4:7], v[44:47], v[16:31]
	v_lshlrev_b32_e32 v4, 16, v106
	v_add_f32_e32 v52, v162, v52
	v_mul_f32_e64 v54, v174, v174
	v_mul_f32_e64 v55, v175, v175
	v_add_f32_e32 v52, v163, v52
	v_lshlrev_b32_e32 v176, 16, v40
	v_and_b32_e32 v177, 0xffff0000, v40
	v_add_f32_e32 v52, v54, v52
	s_nop 3
	v_add_f32_e32 v5, v143, v16
	v_mul_f32_e32 v4, v5, v4
	v_and_b32_e32 v5, 0xffff0000, v106
	v_add_f32_e32 v6, v143, v17
	v_mul_f32_e32 v5, v6, v5
	v_lshlrev_b32_e32 v6, 16, v107
	v_add_f32_e32 v7, v143, v18
	v_mul_f32_e32 v6, v7, v6
	v_and_b32_e32 v7, 0xffff0000, v107
	v_add_f32_e32 v9, v143, v19
	v_mul_f32_e32 v7, v9, v7
	v_mul_f32_e32 v9, v5, v5
	v_fmac_f32_e32 v9, v4, v4
	v_cvt_pk_bf16_f32 v126, v4, v5
	v_lshlrev_b32_e32 v4, 16, v104
	v_add_f32_e32 v5, v143, v20
	v_mul_f32_e32 v20, v5, v4
	v_and_b32_e32 v4, 0xffff0000, v104
	v_add_f32_e32 v5, v143, v21
	v_mul_f32_e32 v10, v7, v7
	v_mul_f32_e32 v21, v5, v4
	v_lshlrev_b32_e32 v4, 16, v105
	v_add_f32_e32 v5, v143, v22
	v_fmac_f32_e32 v10, v6, v6
	v_cvt_pk_bf16_f32 v125, v6, v7
	v_mul_f32_e32 v22, v5, v4
	ds_read_b128 v[4:7], v122 offset:8704
	ds_read_b128 v[16:19], v122 offset:8736
	v_add_f32_e32 v9, v9, v10
	v_add_f32_e32 v88, v8, v9
	v_and_b32_e32 v8, 0xffff0000, v105
	v_add_f32_e32 v9, v143, v23
	v_mul_f32_e32 v23, v9, v8
	v_mul_f32_e32 v8, v21, v21
	v_mul_f32_e32 v9, v23, v23
	v_fmac_f32_e32 v8, v20, v20
	v_fmac_f32_e32 v9, v22, v22
	v_add_f32_e32 v89, v8, v9
	s_waitcnt lgkmcnt(1)
	v_mfma_f32_32x32x16_bf16 v[0:15], v[4:7], v[0:3], 0
	v_cvt_pk_bf16_f32 v136, v20, v21
	v_lshlrev_b32_e32 v20, 16, v102
	v_add_f32_e32 v21, v143, v24
	v_cvt_pk_bf16_f32 v133, v22, v23
	v_mul_f32_e32 v24, v21, v20
	ds_read_b128 v[20:23], v122 offset:8768
	v_add_f32_e32 v88, v89, v88
	s_waitcnt lgkmcnt(1)
	v_mfma_f32_32x32x16_bf16 v[0:15], v[16:19], v[72:75], v[0:15]
	v_and_b32_e32 v16, 0xffff0000, v102
	v_add_f32_e32 v17, v143, v25
	v_mul_f32_e32 v25, v17, v16
	v_lshlrev_b32_e32 v16, 16, v103
	v_add_f32_e32 v17, v143, v26
	v_mul_f32_e32 v26, v17, v16
	ds_read_b128 v[16:19], v122 offset:8800
	s_waitcnt lgkmcnt(1)
	v_mfma_f32_32x32x16_bf16 v[0:15], v[20:23], v[68:71], v[0:15]
	v_and_b32_e32 v20, 0xffff0000, v103
	v_add_f32_e32 v21, v143, v27
	v_mul_f32_e32 v27, v21, v20
	ds_read_b128 v[20:23], v122 offset:8832
	v_mul_f32_e32 v68, v25, v25
	v_mul_f32_e32 v69, v27, v27
	v_fmac_f32_e32 v68, v24, v24
	s_waitcnt lgkmcnt(1)
	v_mfma_f32_32x32x16_bf16 v[0:15], v[16:19], v[64:67], v[0:15]
	v_fmac_f32_e32 v69, v26, v26
	v_add_f32_e32 v16, v68, v69
	v_add_f32_e32 v64, v16, v88
	ds_read_b128 v[16:19], v122 offset:8864
	v_cvt_pk_bf16_f32 v137, v24, v25
	v_lshlrev_b32_e32 v24, 16, v100
	v_cvt_pk_bf16_f32 v134, v26, v27
	s_waitcnt lgkmcnt(1)
	v_mfma_f32_32x32x16_bf16 v[0:15], v[20:23], v[60:63], v[0:15]
	v_add_f32_e32 v20, v143, v28
	v_mul_f32_e32 v24, v20, v24
	v_and_b32_e32 v20, 0xffff0000, v100
	v_add_f32_e32 v21, v143, v29
	v_mul_f32_e32 v25, v21, v20
	ds_read_b128 v[20:23], v122 offset:8896
	v_lshlrev_b32_e32 v26, 16, v101
	s_waitcnt lgkmcnt(1)
; #define LAS __attribute__((address_space(3)))
; __device__ __forceinline__ void gmlp_tile(const Ctx& C, int T, LAS unsigned char* lds, int wave, int lane, int tid) {
;     ...
;     for (int h = 0; h < 4; ++h) {
;         bfx8 wf[8];
;         const bf16* wrow = Weff + ((size_t)(mode * 4 + h) * 128 + t) * 128 + 8 * hh;
; #pragma unroll
;         for (int ks = 0; ks < 8; ++ks) wf[ks] = *(const bfx8*)(wrow + 16 * ks);
;         v2u uw[2][4];
; #pragma unroll
;         for (int dbi = 0; dbi < 2; ++dbi)
; #pragma unroll
;             for (int rg = 0; rg < 4; ++rg) uw[dbi][rg] = *(const v2u*)(zt + h * 128 + 32 * (2 * dh + dbi) + 8 * rg + 4 * hh);
;         const float bias = C.in(13)[h * 128 + (mode ? (t & 15) : t)];
;         v4f gvv[8];
;         { const float* gvp = C.in(11) + h * 128 + q * 32;
; #pragma unroll
;           for (int i = 0; i < 8; ++i) gvv[i] = *(const v4f*)(gvp + 4 * i); }
;         __syncthreads();
;         {
;             float v[32]; float s = 0.f;
; #pragma unroll
;             for (int i = 0; i < 4; ++i) { const v4u w = vraw[i];
;                 v[8 * i + 0] = bf_lo(w.x); v[8 * i + 1] = bf_hi(w.x); v[8 * i + 2] = bf_lo(w.y); v[8 * i + 3] = bf_hi(w.y);
;                 v[8 * i + 4] = bf_lo(w.z); v[8 * i + 5] = bf_hi(w.z); v[8 * i + 6] = bf_lo(w.w); v[8 * i + 7] = bf_hi(w.w); }
;             if (h < 3) {
; #pragma unroll
;     ...
; #pragma unroll
;         for (int dbi = 0; dbi < 2; ++dbi) {
;             const int db = 2 * dh + dbi;
;             v16f acc;
; #pragma unroll
;             for (int r = 0; r < 16; ++r) acc[r] = 0.f;
; #pragma unroll
;             for (int ks = 0; ks < 8; ++ks) {
;                 const bfx8 va = *(const LAS bfx8*)(VT + (32 * db + tl) * VT_STRIDE + 16 * ks + 8 * hh);
;                 acc = __builtin_amdgcn_mfma_f32_32x32x16_bf16(va, wf[ks], acc, 0, 0, 0);
;             }
; #pragma unroll
;             for (int rg = 0; rg < 4; ++rg) {
;                 const v2u u2 = uw[dbi][rg];
;                 const float o0 = bf_lo(u2.x) * (acc[4 * rg + 0] + bias), o1 = bf_hi(u2.x) * (acc[4 * rg + 1] + bias);
;                 const float o2 = bf_lo(u2.y) * (acc[4 * rg + 2] + bias), o3 = bf_hi(u2.y) * (acc[4 * rg + 3] + bias);
;                 ssq += (o0 * o0 + o1 * o1) + (o2 * o2 + o3 * o3);
;                 outp[h][dbi][2 * rg] = cvt_pk_nv(o0, o1); outp[h][dbi][2 * rg + 1] = cvt_pk_nv(o2, o3);
;             }
;         }
	v_mfma_f32_32x32x16_bf16 v[0:15], v[16:19], v[56:59], v[0:15]
	v_add_f32_e32 v16, v143, v30
	v_mul_f32_e32 v26, v16, v26
	v_and_b32_e32 v16, 0xffff0000, v101
	v_add_f32_e32 v17, v143, v31
	v_mul_f32_e32 v27, v17, v16
	ds_read_b128 v[16:19], v122 offset:8928
	v_mul_f32_e32 v28, v25, v25
	s_waitcnt lgkmcnt(1)
	v_mfma_f32_32x32x16_bf16 v[0:15], v[20:23], v[48:51], v[0:15]
	v_mul_f32_e32 v20, v27, v27
	v_fmac_f32_e32 v28, v24, v24
	v_fmac_f32_e32 v20, v26, v26
	v_add_f32_e32 v20, v28, v20
	v_add_f32_e32 v20, v20, v64
	v_cvt_pk_bf16_f32 v138, v24, v25
	v_cvt_pk_bf16_f32 v135, v26, v27
	s_waitcnt lgkmcnt(0)
	v_mfma_f32_32x32x16_bf16 v[0:15], v[16:19], v[44:47], v[0:15]
	v_lshlrev_b32_e32 v16, 16, v98
	v_mul_f32_e64 v164, v176, v176
	v_mul_f32_e64 v165, v177, v177
	v_add_f32_e32 v52, v55, v52
	v_lshlrev_b32_e32 v178, 16, v41
	v_and_b32_e32 v179, 0xffff0000, v41
	v_add_f32_e32 v52, v164, v52
	v_pk_mul_f32 v[40:41], v[178:179], v[178:179]
	s_nop 3
	v_add_f32_e32 v0, v143, v0
	v_mul_f32_e32 v18, v0, v16
	v_and_b32_e32 v0, 0xffff0000, v98
	v_add_f32_e32 v1, v143, v1
	v_mul_f32_e32 v19, v1, v0
	v_lshlrev_b32_e32 v0, 16, v99
	v_add_f32_e32 v1, v143, v2
	v_add_co_u32_e32 v16, vcc, s0, v78
	v_mul_f32_e32 v21, v1, v0
	v_and_b32_e32 v0, 0xffff0000, v99
	v_add_f32_e32 v1, v143, v3
	v_addc_co_u32_e32 v17, vcc, 0, v79, vcc
	s_mov_b64 s[0:1], s[80:81]
	v_mul_f32_e32 v22, v1, v0
	global_load_dwordx4 v[0:3], v[16:17], off offset:-3584
	global_load_dwordx4 v[72:75], v[16:17], off offset:-2560
	global_load_dwordx4 v[68:71], v[16:17], off offset:-1536
	global_load_dwordx4 v[64:67], v[16:17], off offset:-512
	global_load_dwordx4 v[60:63], v[16:17], off offset:512
	global_load_dwordx4 v[56:59], v[16:17], off offset:1536
	global_load_dwordx4 v[48:51], v[16:17], off offset:2560
	global_load_dwordx4 v[44:47], v[16:17], off offset:3584
	global_load_dwordx2 v[106:107], v[80:81], off offset:512
	global_load_dwordx2 v[104:105], v[80:81], off offset:528
	global_load_dwordx2 v[102:103], v[80:81], off offset:544
	global_load_dwordx2 v[100:101], v[80:81], off offset:560
	global_load_dwordx2 v[98:99], v[80:81], off offset:576
	global_load_dwordx2 v[96:97], v[80:81], off offset:592
	global_load_dwordx2 v[92:93], v[80:81], off offset:608
	global_load_dwordx2 v[88:89], v[80:81], off offset:624
	s_load_dwordx2 s[0:1], s[0:1], 0x68
	v_mul_f32_e32 v23, v19, v19
	v_mul_f32_e32 v16, v22, v22
	v_fmac_f32_e32 v23, v18, v18
	v_fmac_f32_e32 v16, v21, v21
	s_waitcnt lgkmcnt(0)
	global_load_dword v151, v124, s[0:1] offset:1024
	s_mov_b64 s[0:1], s[80:81]
	s_load_dwordx2 s[12:13], s[0:1], 0x58
	v_add_f32_e32 v16, v23, v16
	v_add_f32_e32 v141, v20, v16
	v_cvt_pk_bf16_f32 v139, v21, v22
	s_waitcnt lgkmcnt(0)
	global_load_dwordx4 v[20:23], v76, s[12:13] offset:1072
	global_load_dwordx4 v[24:27], v76, s[12:13] offset:1056
	global_load_dwordx4 v[28:31], v76, s[12:13] offset:1040
	global_load_dwordx4 v[144:147], v76, s[12:13] offset:1024
	global_load_dwordx4 v[152:155], v76, s[12:13] offset:1104
	global_load_dwordx4 v[156:159], v76, s[12:13] offset:1088
	v_add_f32_e32 v52, v165, v52
	v_add_f32_e32 v40, v40, v52
	v_add_f32_e32 v40, v41, v40
	v_add_f32_e32 v40, v166, v40
	v_add_f32_e32 v40, v167, v40
	global_load_dwordx4 v[160:163], v76, s[12:13] offset:1136
	global_load_dwordx4 v[164:167], v76, s[12:13] offset:1120
	v_lshlrev_b32_e32 v190, 16, v43
	v_and_b32_e32 v191, 0xffff0000, v43
	v_pk_mul_f32 v[42:43], v[190:191], v[190:191]
	v_lshlrev_b32_e32 v192, 16, v36
	v_and_b32_e32 v193, 0xffff0000, v36
	v_add_f32_e32 v40, v42, v40
	v_pk_mul_f32 v[194:195], v[192:193], v[192:193]
	v_add_f32_e32 v40, v43, v40
	v_lshlrev_b32_e32 v196, 16, v37
	v_and_b32_e32 v197, 0xffff0000, v37
	v_add_f32_e32 v40, v194, v40
	v_pk_mul_f32 v[36:37], v[196:197], v[196:197]
	v_add_f32_e32 v40, v195, v40
	v_lshlrev_b32_e32 v198, 16, v38
	v_and_b32_e32 v199, 0xffff0000, v38
	v_add_f32_e32 v36, v36, v40
	v_pk_mul_f32 v[200:201], v[198:199], v[198:199]
	v_add_f32_e32 v36, v37, v36
	v_lshlrev_b32_e32 v202, 16, v39
	v_and_b32_e32 v203, 0xffff0000, v39
	v_add_f32_e32 v36, v200, v36
	v_pk_mul_f32 v[38:39], v[202:203], v[202:203]
	v_add_f32_e32 v36, v201, v36
	v_and_b32_e32 v205, 0xffff0000, v32
	v_add_f32_e32 v36, v38, v36
	v_pk_mul_f32 v[206:207], v[204:205], v[204:205]
	v_add_f32_e32 v36, v39, v36
	v_lshlrev_b32_e32 v208, 16, v33
	v_and_b32_e32 v209, 0xffff0000, v33
	v_add_f32_e32 v36, v206, v36
	v_pk_mul_f32 v[32:33], v[208:209], v[208:209]
	v_add_f32_e32 v36, v207, v36
	v_cvt_pk_bf16_f32 v140, v18, v19
	v_and_b32_e32 v18, 0xffff0000, v34
	v_lshlrev_b32_e32 v19, 16, v34
	v_add_f32_e32 v32, v32, v36
	v_pk_mul_f32 v[148:149], v[18:19], v[18:19]
	v_add_f32_e32 v32, v33, v32
	v_and_b32_e32 v16, 0xffff0000, v35
	v_lshlrev_b32_e32 v17, 16, v35
	v_add_f32_e32 v32, v149, v32
	v_pk_mul_f32 v[34:35], v[16:17], v[16:17]
	v_add_f32_e32 v32, v148, v32
	v_add_f32_e32 v32, v35, v32
	v_add_f32_e32 v32, v34, v32
	ds_bpermute_b32 v33, v183, v32
	v_lshlrev_b32_e32 v142, 16, v94
	v_add_f32_e32 v4, v143, v4
	v_mul_f32_e32 v142, v4, v142
	v_and_b32_e32 v4, 0xffff0000, v94
	v_add_f32_e32 v5, v143, v5
	v_mul_f32_e32 v94, v5, v4
	s_waitcnt lgkmcnt(0)
	v_add_f32_e32 v4, v32, v33
	ds_bpermute_b32 v5, v184, v4
	s_waitcnt lgkmcnt(0)
	s_barrier
; __device__ __forceinline__ float bf_lo(unsigned w) { return __uint_as_float(w << 16); }
; __device__ __forceinline__ float bf_hi(unsigned w) { return __uint_as_float(w & 0xffff0000u); }
; __device__ __forceinline__ bf16 f2bf(float f) { return (bf16)(cvt_pk_nv(f, 0.f) & 0xffffu); }
;     __device__ __forceinline__ float* out() const { return (float*)karg_in(33); }
; __device__ __forceinline__ void gmlp_tile(const Ctx& C, int T, LAS unsigned char* lds, int wave, int lane, int tid) {
;     ...
;         __syncthreads();
;         {
;             float v[32]; float s = 0.f;
; #pragma unroll
;             for (int i = 0; i < 4; ++i) { const v4u w = vraw[i];
;                 v[8 * i + 0] = bf_lo(w.x); v[8 * i + 1] = bf_hi(w.x); v[8 * i + 2] = bf_lo(w.y); v[8 * i + 3] = bf_hi(w.y);
;                 v[8 * i + 4] = bf_lo(w.z); v[8 * i + 5] = bf_hi(w.z); v[8 * i + 6] = bf_lo(w.w); v[8 * i + 7] = bf_hi(w.w); }
;             if (h < 3) {
; #pragma unroll
;                 for (int i = 0; i < 4; ++i) vraw[i] = *(const v4u*)(vsrc + (h + 1) * 128 + 8 * i);
;             }
; #pragma unroll
;             for (int i = 0; i < 32; ++i) s += v[i] * v[i];
;             s += __shfl_xor(s, 1); s += __shfl_xor(s, 2);
;             const float r = rsqrtf(s * (1.f / 128.f) + EPS);
; #pragma unroll
;             for (int i = 0; i < 32; ++i) { v[i] = v[i] * r * gvv[i >> 2][i & 3]; VT[(q * 32 + i) * VT_STRIDE + row] = f2bf(v[i]); }
;             if (mode) { float* ov = C.out() + OFF_V_S + (size_t)row * AW + h * 128 + q * 32;
; #pragma unroll
;                 for (int i = 0; i < 8; ++i) *(v4f*)(ov + 4 * i) = (v4f){v[4 * i], v[4 * i + 1], v[4 * i + 2], v[4 * i + 3]}; }
;         }
;         __syncthreads();
	global_load_dwordx4 v[32:35], v[84:85], off offset:816
	global_load_dwordx4 v[36:39], v[84:85], off offset:800
	global_load_dwordx4 v[40:43], v[84:85], off offset:784
	global_load_dwordx4 v[52:55], v[84:85], off offset:768
	v_add_f32_e32 v4, v4, v5
	v_fmamk_f32 v4, v4, 0x3c000000, v110
	v_mul_f32_e32 v5, 0x4b800000, v4
	v_cmp_gt_f32_e32 vcc, s11, v4
	s_mov_b64 s[0:1], s[80:81]
	v_add_f32_e32 v8, v143, v8
	v_cndmask_b32_e32 v4, v4, v5, vcc
	v_rsq_f32_e32 v4, v4
	s_waitcnt vmcnt(3)
	v_lshlrev_b32_e32 v210, 16, v32
	v_mul_f32_e32 v5, 0x45800000, v4
	v_cndmask_b32_e32 v4, v4, v5, vcc
	v_pk_mul_f32 v[84:85], v[4:5], v[168:169] op_sel_hi:[0,1]
	v_pk_mul_f32 v[144:145], v[144:145], v[84:85]
	v_and_b32_e32 v211, 0xffff0000, v32
	v_cvt_pk_bf16_f32 v5, v144, v77
	ds_write_b16 v123, v5
	v_cvt_pk_bf16_f32 v5, v145, v77
	ds_write_b16 v123, v5 offset:272
	v_pk_mul_f32 v[84:85], v[4:5], v[170:171] op_sel_hi:[0,1]
	v_pk_mul_f32 v[146:147], v[146:147], v[84:85]
	v_pk_mul_f32 v[212:213], v[210:211], v[210:211]
	v_cvt_pk_bf16_f32 v5, v146, v77
	ds_write_b16 v123, v5 offset:544
	v_cvt_pk_bf16_f32 v5, v147, v77
	ds_write_b16 v123, v5 offset:816
	v_pk_mul_f32 v[84:85], v[4:5], v[172:173] op_sel_hi:[0,1]
	v_pk_mul_f32 v[28:29], v[28:29], v[84:85]
	s_waitcnt vmcnt(0)
	v_lshlrev_b32_e32 v172, 16, v54
	v_cvt_pk_bf16_f32 v5, v28, v77
	ds_write_b16 v123, v5 offset:1088
	v_cvt_pk_bf16_f32 v5, v29, v77
	ds_write_b16 v123, v5 offset:1360
	v_pk_mul_f32 v[84:85], v[4:5], v[174:175] op_sel_hi:[0,1]
	v_pk_mul_f32 v[30:31], v[30:31], v[84:85]
	v_and_b32_e32 v173, 0xffff0000, v54
	v_cvt_pk_bf16_f32 v5, v30, v77
	ds_write_b16 v123, v5 offset:1632
	v_cvt_pk_bf16_f32 v5, v31, v77
	ds_write_b16 v123, v5 offset:1904
	v_pk_mul_f32 v[84:85], v[4:5], v[176:177] op_sel_hi:[0,1]
	v_pk_mul_f32 v[24:25], v[24:25], v[84:85]
	v_pk_mul_f32 v[174:175], v[172:173], v[172:173]
	v_cvt_pk_bf16_f32 v5, v24, v77
	ds_write_b16 v123, v5 offset:2176
	v_cvt_pk_bf16_f32 v5, v25, v77
	ds_write_b16 v123, v5 offset:2448
	v_pk_mul_f32 v[84:85], v[4:5], v[178:179] op_sel_hi:[0,1]
	v_pk_mul_f32 v[26:27], v[26:27], v[84:85]
	v_lshlrev_b32_e32 v54, 16, v55
	v_cvt_pk_bf16_f32 v5, v26, v77
	ds_write_b16 v123, v5 offset:2720
	v_cvt_pk_bf16_f32 v5, v27, v77
	ds_write_b16 v123, v5 offset:2992
	v_pk_mul_f32 v[84:85], v[4:5], v[180:181] op_sel_hi:[0,1]
	v_pk_mul_f32 v[20:21], v[20:21], v[84:85]
	v_and_b32_e32 v55, 0xffff0000, v55
	v_cvt_pk_bf16_f32 v5, v20, v77
	ds_write_b16 v123, v5 offset:3264
	v_cvt_pk_bf16_f32 v5, v21, v77
	ds_write_b16 v123, v5 offset:3536
	v_pk_mul_f32 v[84:85], v[4:5], v[190:191] op_sel_hi:[0,1]
	v_pk_mul_f32 v[22:23], v[22:23], v[84:85]
	v_pk_mul_f32 v[176:177], v[54:55], v[54:55]
	v_cvt_pk_bf16_f32 v5, v22, v77
	ds_write_b16 v123, v5 offset:3808
	v_cvt_pk_bf16_f32 v5, v23, v77
	ds_write_b16 v123, v5 offset:4080
	v_pk_mul_f32 v[84:85], v[4:5], v[192:193] op_sel_hi:[0,1]
	v_pk_mul_f32 v[156:157], v[156:157], v[84:85]
	v_lshlrev_b32_e32 v178, 16, v40
	v_cvt_pk_bf16_f32 v5, v156, v77
	ds_write_b16 v123, v5 offset:4352
	v_cvt_pk_bf16_f32 v5, v157, v77
	ds_write_b16 v123, v5 offset:4624
	v_pk_mul_f32 v[84:85], v[4:5], v[196:197] op_sel_hi:[0,1]
	v_pk_mul_f32 v[158:159], v[158:159], v[84:85]
	v_and_b32_e32 v179, 0xffff0000, v40
	v_cvt_pk_bf16_f32 v5, v158, v77
	ds_write_b16 v123, v5 offset:4896
	v_cvt_pk_bf16_f32 v5, v159, v77
	ds_write_b16 v123, v5 offset:5168
	v_pk_mul_f32 v[84:85], v[4:5], v[198:199] op_sel_hi:[0,1]
	v_pk_mul_f32 v[152:153], v[152:153], v[84:85]
	v_pk_mul_f32 v[180:181], v[178:179], v[178:179]
	v_cvt_pk_bf16_f32 v5, v152, v77
	ds_write_b16 v123, v5 offset:5440
	v_cvt_pk_bf16_f32 v5, v153, v77
	ds_write_b16 v123, v5 offset:5712
	v_pk_mul_f32 v[84:85], v[4:5], v[202:203] op_sel_hi:[0,1]
	v_pk_mul_f32 v[154:155], v[154:155], v[84:85]
	v_lshlrev_b32_e32 v190, 16, v41
	v_cvt_pk_bf16_f32 v5, v154, v77
	ds_write_b16 v123, v5 offset:5984
	v_cvt_pk_bf16_f32 v5, v155, v77
	ds_write_b16 v123, v5 offset:6256
	v_pk_mul_f32 v[84:85], v[4:5], v[204:205] op_sel_hi:[0,1]
	v_pk_mul_f32 v[164:165], v[164:165], v[84:85]
	v_and_b32_e32 v191, 0xffff0000, v41
	v_cvt_pk_bf16_f32 v5, v164, v77
	ds_write_b16 v123, v5 offset:6528
	v_cvt_pk_bf16_f32 v5, v165, v77
	ds_write_b16 v123, v5 offset:6800
	v_pk_mul_f32 v[84:85], v[4:5], v[208:209] op_sel_hi:[0,1]
	v_pk_mul_f32 v[166:167], v[166:167], v[84:85]
	v_pk_mul_f32 v[40:41], v[190:191], v[190:191]
	v_cvt_pk_bf16_f32 v5, v166, v77
	ds_write_b16 v123, v5 offset:7072
	v_cvt_pk_bf16_f32 v5, v167, v77
	ds_write_b16 v123, v5 offset:7344
	v_pk_mul_f32 v[18:19], v[4:5], v[18:19] op_sel_hi:[0,1]
	v_pk_mul_f32 v[160:161], v[160:161], v[18:19] op_sel:[0,1] op_sel_hi:[1,0]
	v_lshlrev_b32_e32 v192, 16, v42
	v_cvt_pk_bf16_f32 v5, v160, v77
	ds_write_b16 v123, v5 offset:7616
	v_cvt_pk_bf16_f32 v5, v161, v77
	ds_write_b16 v123, v5 offset:7888
	v_pk_mul_f32 v[4:5], v[4:5], v[16:17] op_sel_hi:[0,1]
	v_pk_mul_f32 v[162:163], v[162:163], v[4:5] op_sel:[0,1] op_sel_hi:[1,0]
	v_add_f32_e32 v5, v143, v6
	v_cvt_pk_bf16_f32 v4, v162, v77
	ds_write_b16 v123, v4 offset:8160
	v_cvt_pk_bf16_f32 v4, v163, v77
	ds_write_b16 v123, v4 offset:8432
	s_load_dwordx2 s[0:1], s[0:1], 0x108
	v_lshlrev_b32_e32 v4, 16, v95
	v_mul_f32_e32 v84, v5, v4
	v_and_b32_e32 v6, 0xffff0000, v95
	v_and_b32_e32 v193, 0xffff0000, v42
	s_waitcnt lgkmcnt(0)
	v_lshl_add_u64 v[4:5], s[0:1], 0, v[82:83]
	v_lshl_add_u64 v[4:5], v[4:5], 0, v[76:77]
	s_mov_b64 s[0:1], 0x80a8400
	v_lshl_add_u64 v[16:17], v[4:5], 0, s[0:1]
	v_add_co_u32_e32 v4, vcc, s16, v4
	s_mov_b32 s0, 0x2938000
	s_nop 0
	v_addc_co_u32_e32 v5, vcc, 0, v5, vcc
	global_store_dwordx4 v[4:5], v[144:147], off offset:1024
	global_store_dwordx4 v[16:17], v[28:31], off offset:16
	global_store_dwordx4 v[16:17], v[24:27], off offset:32
	global_store_dwordx4 v[16:17], v[20:23], off offset:48
	global_store_dwordx4 v[16:17], v[156:159], off offset:64
	global_store_dwordx4 v[16:17], v[152:155], off offset:80
	global_store_dwordx4 v[16:17], v[164:167], off offset:96
	global_store_dwordx4 v[16:17], v[160:163], off offset:112
	s_barrier
; __device__ __forceinline__ float bf_lo(unsigned w) { return __uint_as_float(w << 16); }
; __device__ __forceinline__ float bf_hi(unsigned w) { return __uint_as_float(w & 0xffff0000u); }
; #define LAS __attribute__((address_space(3)))
; __device__ __forceinline__ unsigned cvt_pk_nv(float lo, float hi) { unsigned r; asm("v_cvt_pk_bf16_f32 %0, %1, %2" : "=v"(r) : "v"(lo), "v"(hi)); return r; }
; __device__ __forceinline__ void gmlp_tile(const Ctx& C, int T, LAS unsigned char* lds, int wave, int lane, int tid) {
;     ...
; #pragma unroll
;         for (int dbi = 0; dbi < 2; ++dbi) {
;             const int db = 2 * dh + dbi;
;             v16f acc;
; #pragma unroll
;             for (int r = 0; r < 16; ++r) acc[r] = 0.f;
; #pragma unroll
;             for (int ks = 0; ks < 8; ++ks) {
;                 const bfx8 va = *(const LAS bfx8*)(VT + (32 * db + tl) * VT_STRIDE + 16 * ks + 8 * hh);
;                 acc = __builtin_amdgcn_mfma_f32_32x32x16_bf16(va, wf[ks], acc, 0, 0, 0);
;             }
; #pragma unroll
;             for (int rg = 0; rg < 4; ++rg) {
;                 const v2u u2 = uw[dbi][rg];
;                 const float o0 = bf_lo(u2.x) * (acc[4 * rg + 0] + bias), o1 = bf_hi(u2.x) * (acc[4 * rg + 1] + bias);
;                 const float o2 = bf_lo(u2.y) * (acc[4 * rg + 2] + bias), o3 = bf_hi(u2.y) * (acc[4 * rg + 3] + bias);
;                 ssq += (o0 * o0 + o1 * o1) + (o2 * o2 + o3 * o3);
;                 outp[h][dbi][2 * rg] = cvt_pk_nv(o0, o1); outp[h][dbi][2 * rg + 1] = cvt_pk_nv(o2, o3);
;             }
;         }
	ds_read_b128 v[16:19], v122
	v_add_f32_e32 v4, v143, v7
	v_mul_f32_e32 v85, v4, v6
	v_mul_f32_e32 v4, v94, v94
	v_mul_f32_e32 v5, v85, v85
	v_fmac_f32_e32 v4, v142, v142
	v_fmac_f32_e32 v5, v84, v84
	v_add_f32_e32 v95, v4, v5
	ds_read_b128 v[4:7], v122 offset:32
	s_waitcnt lgkmcnt(1)
	v_mfma_f32_32x32x16_bf16 v[16:31], v[16:19], v[0:3], 0
	ds_read_b128 v[146:149], v122 offset:64
	v_add_f32_e32 v95, v95, v141
	v_cvt_pk_bf16_f32 v141, v84, v85
	v_lshlrev_b32_e32 v84, 16, v90
	v_mul_f32_e32 v84, v8, v84
	v_and_b32_e32 v8, 0xffff0000, v91
	v_cvt_pk_bf16_f32 v144, v142, v94
	s_waitcnt lgkmcnt(1)
	v_mfma_f32_32x32x16_bf16 v[16:31], v[4:7], v[72:75], v[16:31]
	v_and_b32_e32 v4, 0xffff0000, v90
	v_add_f32_e32 v5, v143, v9
	v_mul_f32_e32 v85, v5, v4
	v_lshlrev_b32_e32 v4, 16, v91
	v_add_f32_e32 v5, v143, v10
	v_mul_f32_e32 v90, v5, v4
	ds_read_b128 v[4:7], v122 offset:96
	s_waitcnt lgkmcnt(1)
	v_mfma_f32_32x32x16_bf16 v[16:31], v[146:149], v[68:71], v[16:31]
	v_add_f32_e32 v9, v143, v11
	v_mul_f32_e32 v91, v9, v8
	ds_read_b128 v[8:11], v122 offset:128
	v_mul_f32_e32 v94, v85, v85
	v_mul_f32_e32 v142, v91, v91
	v_fmac_f32_e32 v94, v84, v84
	v_fmac_f32_e32 v142, v90, v90
	s_waitcnt lgkmcnt(1)
	v_mfma_f32_32x32x16_bf16 v[16:31], v[4:7], v[64:67], v[16:31]
	v_add_f32_e32 v4, v94, v142
	v_add_f32_e32 v94, v4, v95
	ds_read_b128 v[4:7], v122 offset:160
	v_cvt_pk_bf16_f32 v145, v84, v85
	v_lshlrev_b32_e32 v84, 16, v86
	v_lshlrev_b32_e32 v166, 16, v52
	v_and_b32_e32 v167, 0xffff0000, v52
	s_waitcnt lgkmcnt(1)
	v_mfma_f32_32x32x16_bf16 v[16:31], v[8:11], v[60:63], v[16:31]
	v_add_f32_e32 v8, v143, v12
	v_mul_f32_e32 v12, v8, v84
	v_and_b32_e32 v8, 0xffff0000, v86
	v_add_f32_e32 v9, v143, v13
	v_mul_f32_e32 v13, v9, v8
	ds_read_b128 v[8:11], v122 offset:192
	v_lshlrev_b32_e32 v84, 16, v87
	s_waitcnt lgkmcnt(1)
	v_mfma_f32_32x32x16_bf16 v[16:31], v[4:7], v[56:59], v[16:31]
	v_add_f32_e32 v4, v143, v14
	v_mul_f32_e32 v14, v4, v84
	v_and_b32_e32 v4, 0xffff0000, v87
	v_add_f32_e32 v5, v143, v15
	v_mul_f32_e32 v15, v5, v4
	ds_read_b128 v[4:7], v122 offset:224
	v_mul_f32_e32 v84, v13, v13
	s_waitcnt lgkmcnt(1)
	v_mfma_f32_32x32x16_bf16 v[16:31], v[8:11], v[48:51], v[16:31]
	v_mul_f32_e32 v8, v15, v15
	v_fmac_f32_e32 v84, v12, v12
	v_fmac_f32_e32 v8, v14, v14
	v_add_f32_e32 v8, v84, v8
	v_add_f32_e32 v8, v8, v94
	v_cvt_pk_bf16_f32 v146, v12, v13
	v_cvt_pk_bf16_f32 v143, v14, v15
	s_waitcnt lgkmcnt(0)
	v_mfma_f32_32x32x16_bf16 v[16:31], v[4:7], v[44:47], v[16:31]
	v_lshlrev_b32_e32 v4, 16, v106
	v_mul_f32_e64 v168, v166, v166
	v_mul_f32_e64 v169, v167, v167
	v_lshlrev_b32_e32 v52, 16, v53
	v_and_b32_e32 v53, 0xffff0000, v53
	v_pk_mul_f32 v[170:171], v[52:53], v[52:53]
	v_add_f32_e32 v168, v168, v169
	v_add_f32_e32 v168, v170, v168
	s_nop 3
	v_add_f32_e32 v5, v151, v16
	v_mul_f32_e32 v4, v5, v4
	v_and_b32_e32 v5, 0xffff0000, v106
	v_add_f32_e32 v6, v151, v17
	v_mul_f32_e32 v5, v6, v5
	v_lshlrev_b32_e32 v6, 16, v107
	v_add_f32_e32 v7, v151, v18
	v_mul_f32_e32 v6, v7, v6
	v_and_b32_e32 v7, 0xffff0000, v107
	v_add_f32_e32 v9, v151, v19
	v_mul_f32_e32 v7, v9, v7
	v_mul_f32_e32 v9, v5, v5
	v_fmac_f32_e32 v9, v4, v4
	v_cvt_pk_bf16_f32 v107, v4, v5
	v_lshlrev_b32_e32 v4, 16, v104
	v_add_f32_e32 v5, v151, v20
	v_mul_f32_e32 v20, v5, v4
	v_and_b32_e32 v4, 0xffff0000, v104
	v_add_f32_e32 v5, v151, v21
	v_mul_f32_e32 v10, v7, v7
	v_mul_f32_e32 v21, v5, v4
	v_lshlrev_b32_e32 v4, 16, v105
	v_add_f32_e32 v5, v151, v22
	v_fmac_f32_e32 v10, v6, v6
	v_cvt_pk_bf16_f32 v106, v6, v7
	v_mul_f32_e32 v22, v5, v4
	ds_read_b128 v[4:7], v122 offset:8704
	ds_read_b128 v[16:19], v122 offset:8736
	v_add_f32_e32 v9, v9, v10
	v_add_f32_e32 v84, v8, v9
	v_and_b32_e32 v8, 0xffff0000, v105
	v_add_f32_e32 v9, v151, v23
	v_mul_f32_e32 v23, v9, v8
	v_mul_f32_e32 v8, v21, v21
	v_mul_f32_e32 v9, v23, v23
	v_fmac_f32_e32 v8, v20, v20
	v_fmac_f32_e32 v9, v22, v22
	v_add_f32_e32 v85, v8, v9
	s_waitcnt lgkmcnt(1)
	v_mfma_f32_32x32x16_bf16 v[0:15], v[4:7], v[0:3], 0
	v_cvt_pk_bf16_f32 v148, v20, v21
	v_lshlrev_b32_e32 v20, 16, v102
	v_add_f32_e32 v21, v151, v24
	v_cvt_pk_bf16_f32 v104, v22, v23
	v_mul_f32_e32 v24, v21, v20
	ds_read_b128 v[20:23], v122 offset:8768
	v_add_f32_e32 v84, v85, v84
	s_waitcnt lgkmcnt(1)
	v_mfma_f32_32x32x16_bf16 v[0:15], v[16:19], v[72:75], v[0:15]
	v_and_b32_e32 v16, 0xffff0000, v102
	v_add_f32_e32 v17, v151, v25
	v_mul_f32_e32 v25, v17, v16
	v_lshlrev_b32_e32 v16, 16, v103
	v_add_f32_e32 v17, v151, v26
	v_mul_f32_e32 v26, v17, v16
	ds_read_b128 v[16:19], v122 offset:8800
	s_waitcnt lgkmcnt(1)
	v_mfma_f32_32x32x16_bf16 v[0:15], v[20:23], v[68:71], v[0:15]
	v_and_b32_e32 v20, 0xffff0000, v103
	v_add_f32_e32 v21, v151, v27
	v_mul_f32_e32 v27, v21, v20
	ds_read_b128 v[20:23], v122 offset:8832
	v_mul_f32_e32 v68, v25, v25
	v_mul_f32_e32 v69, v27, v27
	v_fmac_f32_e32 v68, v24, v24
	s_waitcnt lgkmcnt(1)
	v_mfma_f32_32x32x16_bf16 v[0:15], v[16:19], v[64:67], v[0:15]
	v_fmac_f32_e32 v69, v26, v26
	v_add_f32_e32 v16, v68, v69
	v_add_f32_e32 v64, v16, v84
	ds_read_b128 v[16:19], v122 offset:8864
	v_cvt_pk_bf16_f32 v149, v24, v25
	v_lshlrev_b32_e32 v24, 16, v100
	v_cvt_pk_bf16_f32 v105, v26, v27
	s_waitcnt lgkmcnt(1)
	v_mfma_f32_32x32x16_bf16 v[0:15], v[20:23], v[60:63], v[0:15]
	v_add_f32_e32 v20, v151, v28
	v_mul_f32_e32 v24, v20, v24
	v_and_b32_e32 v20, 0xffff0000, v100
	v_add_f32_e32 v21, v151, v29
	v_mul_f32_e32 v25, v21, v20
	ds_read_b128 v[20:23], v122 offset:8896
	v_lshlrev_b32_e32 v26, 16, v101
	s_waitcnt lgkmcnt(1)
	v_mfma_f32_32x32x16_bf16 v[0:15], v[16:19], v[56:59], v[0:15]
	v_add_f32_e32 v16, v151, v30
	v_mul_f32_e32 v26, v16, v26
	v_and_b32_e32 v16, 0xffff0000, v101
	v_add_f32_e32 v17, v151, v31
	v_mul_f32_e32 v27, v17, v16
	ds_read_b128 v[16:19], v122 offset:8928
	v_mul_f32_e32 v28, v25, v25
	s_waitcnt lgkmcnt(1)
; #define LAS __attribute__((address_space(3)))
; __device__ __forceinline__ void gmlp_tile(const Ctx& C, int T, LAS unsigned char* lds, int wave, int lane, int tid) {
;     ...
;     for (int h = 0; h < 4; ++h) {
;         bfx8 wf[8];
;         const bf16* wrow = Weff + ((size_t)(mode * 4 + h) * 128 + t) * 128 + 8 * hh;
; #pragma unroll
;         for (int ks = 0; ks < 8; ++ks) wf[ks] = *(const bfx8*)(wrow + 16 * ks);
;         v2u uw[2][4];
; #pragma unroll
;         for (int dbi = 0; dbi < 2; ++dbi)
; #pragma unroll
;             for (int rg = 0; rg < 4; ++rg) uw[dbi][rg] = *(const v2u*)(zt + h * 128 + 32 * (2 * dh + dbi) + 8 * rg + 4 * hh);
;         const float bias = C.in(13)[h * 128 + (mode ? (t & 15) : t)];
;         v4f gvv[8];
;         { const float* gvp = C.in(11) + h * 128 + q * 32;
; #pragma unroll
;           for (int i = 0; i < 8; ++i) gvv[i] = *(const v4f*)(gvp + 4 * i); }
;         __syncthreads();
;         {
;             float v[32]; float s = 0.f;
; #pragma unroll
;             for (int i = 0; i < 4; ++i) { const v4u w = vraw[i];
;                 v[8 * i + 0] = bf_lo(w.x); v[8 * i + 1] = bf_hi(w.x); v[8 * i + 2] = bf_lo(w.y); v[8 * i + 3] = bf_hi(w.y);
;                 v[8 * i + 4] = bf_lo(w.z); v[8 * i + 5] = bf_hi(w.z); v[8 * i + 6] = bf_lo(w.w); v[8 * i + 7] = bf_hi(w.w); }
;             if (h < 3) {
; #pragma unroll
;     ...
; #pragma unroll
;         for (int dbi = 0; dbi < 2; ++dbi) {
;             const int db = 2 * dh + dbi;
;             v16f acc;
; #pragma unroll
;             for (int r = 0; r < 16; ++r) acc[r] = 0.f;
; #pragma unroll
;             for (int ks = 0; ks < 8; ++ks) {
;                 const bfx8 va = *(const LAS bfx8*)(VT + (32 * db + tl) * VT_STRIDE + 16 * ks + 8 * hh);
;                 acc = __builtin_amdgcn_mfma_f32_32x32x16_bf16(va, wf[ks], acc, 0, 0, 0);
;             }
; #pragma unroll
;             for (int rg = 0; rg < 4; ++rg) {
;                 const v2u u2 = uw[dbi][rg];
;                 const float o0 = bf_lo(u2.x) * (acc[4 * rg + 0] + bias), o1 = bf_hi(u2.x) * (acc[4 * rg + 1] + bias);
;                 const float o2 = bf_lo(u2.y) * (acc[4 * rg + 2] + bias), o3 = bf_hi(u2.y) * (acc[4 * rg + 3] + bias);
;                 ssq += (o0 * o0 + o1 * o1) + (o2 * o2 + o3 * o3);
;                 outp[h][dbi][2 * rg] = cvt_pk_nv(o0, o1); outp[h][dbi][2 * rg + 1] = cvt_pk_nv(o2, o3);
;             }
;         }
	v_mfma_f32_32x32x16_bf16 v[0:15], v[20:23], v[48:51], v[0:15]
	v_mul_f32_e32 v20, v27, v27
	v_fmac_f32_e32 v28, v24, v24
	v_fmac_f32_e32 v20, v26, v26
	v_add_f32_e32 v20, v28, v20
	v_cvt_pk_bf16_f32 v142, v90, v91
	v_add_f32_e32 v20, v20, v64
	v_add_f32_e32 v168, v171, v168
	s_waitcnt lgkmcnt(0)
	v_mfma_f32_32x32x16_bf16 v[0:15], v[16:19], v[44:47], v[0:15]
	v_lshlrev_b32_e32 v16, 16, v98
	v_add_f32_e32 v168, v174, v168
	v_add_f32_e32 v168, v175, v168
	v_add_f32_e32 v168, v176, v168
	v_add_f32_e32 v168, v177, v168
	v_add_f32_e32 v168, v180, v168
	v_add_f32_e32 v168, v181, v168
	s_nop 4
	v_add_f32_e32 v0, v151, v0
	v_mul_f32_e32 v18, v0, v16
	v_and_b32_e32 v0, 0xffff0000, v98
	v_add_f32_e32 v1, v151, v1
	v_mul_f32_e32 v19, v1, v0
	v_lshlrev_b32_e32 v0, 16, v99
	v_add_f32_e32 v1, v151, v2
	v_add_co_u32_e32 v16, vcc, s0, v78
	v_mul_f32_e32 v21, v1, v0
	v_and_b32_e32 v0, 0xffff0000, v99
	v_add_f32_e32 v1, v151, v3
	v_addc_co_u32_e32 v17, vcc, 0, v79, vcc
	s_mov_b64 s[0:1], s[80:81]
	v_mul_f32_e32 v22, v1, v0
	global_load_dwordx4 v[0:3], v[16:17], off offset:-3584
	global_load_dwordx4 v[72:75], v[16:17], off offset:-2560
	global_load_dwordx4 v[68:71], v[16:17], off offset:-1536
	global_load_dwordx4 v[64:67], v[16:17], off offset:-512
	global_load_dwordx4 v[60:63], v[16:17], off offset:512
	global_load_dwordx4 v[56:59], v[16:17], off offset:1536
	global_load_dwordx4 v[48:51], v[16:17], off offset:2560
	global_load_dwordx4 v[44:47], v[16:17], off offset:3584
	global_load_dwordx2 v[102:103], v[80:81], off offset:768
	global_load_dwordx2 v[100:101], v[80:81], off offset:784
	global_load_dwordx2 v[98:99], v[80:81], off offset:800
	global_load_dwordx2 v[94:95], v[80:81], off offset:816
	global_load_dwordx2 v[90:91], v[80:81], off offset:832
	global_load_dwordx2 v[86:87], v[80:81], off offset:848
	global_load_dwordx2 v[84:85], v[80:81], off offset:864
	global_load_dwordx2 v[78:79], v[80:81], off offset:880
	s_load_dwordx2 s[0:1], s[0:1], 0x68
	v_add_f32_e32 v40, v40, v168
	v_pk_mul_f32 v[194:195], v[192:193], v[192:193]
	v_add_f32_e32 v40, v41, v40
	v_mul_f32_e32 v16, v19, v19
	s_waitcnt lgkmcnt(0)
	global_load_dword v124, v124, s[0:1] offset:1536
	s_mov_b64 s[0:1], s[80:81]
	s_load_dwordx2 s[12:13], s[0:1], 0x58
	v_mul_f32_e32 v17, v22, v22
	v_lshlrev_b32_e32 v196, 16, v43
	v_and_b32_e32 v197, 0xffff0000, v43
	v_add_f32_e32 v40, v194, v40
	v_fmac_f32_e32 v16, v18, v18
	v_fmac_f32_e32 v17, v21, v21
	v_pk_mul_f32 v[42:43], v[196:197], v[196:197]
	v_add_f32_e32 v40, v195, v40
	v_add_f32_e32 v16, v16, v17
	v_lshlrev_b32_e32 v198, 16, v36
	v_and_b32_e32 v199, 0xffff0000, v36
	v_add_f32_e32 v40, v42, v40
	v_cvt_pk_bf16_f32 v150, v24, v25
	v_cvt_pk_bf16_f32 v147, v26, v27
	v_add_f32_e32 v189, v20, v16
	v_cvt_pk_bf16_f32 v80, v21, v22
	s_waitcnt lgkmcnt(0)
	global_load_dwordx4 v[20:23], v76, s[12:13] offset:1584
	global_load_dwordx4 v[24:27], v76, s[12:13] offset:1568
	global_load_dwordx4 v[28:31], v76, s[12:13] offset:1552
	global_load_dwordx4 v[152:155], v76, s[12:13] offset:1536
	global_load_dwordx4 v[156:159], v76, s[12:13] offset:1616
	global_load_dwordx4 v[160:163], v76, s[12:13] offset:1600
	v_pk_mul_f32 v[200:201], v[198:199], v[198:199]
	v_add_f32_e32 v40, v43, v40
	v_lshlrev_b32_e32 v202, 16, v37
	v_and_b32_e32 v203, 0xffff0000, v37
	v_add_f32_e32 v40, v200, v40
	v_pk_mul_f32 v[36:37], v[202:203], v[202:203]
	v_add_f32_e32 v40, v201, v40
	v_lshlrev_b32_e32 v204, 16, v38
	v_and_b32_e32 v205, 0xffff0000, v38
	v_add_f32_e32 v36, v36, v40
	v_pk_mul_f32 v[206:207], v[204:205], v[204:205]
	v_add_f32_e32 v36, v37, v36
	v_lshlrev_b32_e32 v208, 16, v39
	v_and_b32_e32 v209, 0xffff0000, v39
	v_add_f32_e32 v36, v206, v36
	v_pk_mul_f32 v[38:39], v[208:209], v[208:209]
	v_add_f32_e32 v36, v207, v36
	v_add_f32_e32 v36, v38, v36
	v_add_f32_e32 v36, v39, v36
	v_lshlrev_b32_e32 v214, 16, v33
	v_and_b32_e32 v215, 0xffff0000, v33
	v_add_f32_e32 v36, v212, v36
	v_pk_mul_f32 v[32:33], v[214:215], v[214:215]
	v_add_f32_e32 v36, v213, v36
	v_cvt_pk_bf16_f32 v81, v18, v19
	v_and_b32_e32 v18, 0xffff0000, v34
	v_lshlrev_b32_e32 v19, 16, v34
	v_add_f32_e32 v32, v32, v36
	v_pk_mul_f32 v[164:165], v[18:19], v[18:19]
	v_add_f32_e32 v32, v33, v32
	v_and_b32_e32 v16, 0xffff0000, v35
	v_lshlrev_b32_e32 v17, 16, v35
	v_add_f32_e32 v32, v165, v32
	v_pk_mul_f32 v[34:35], v[16:17], v[16:17]
	v_add_f32_e32 v32, v164, v32
	v_add_f32_e32 v32, v35, v32
	v_add_f32_e32 v32, v34, v32
	ds_bpermute_b32 v33, v183, v32
	v_lshlrev_b32_e32 v34, 16, v96
	v_add_f32_e32 v4, v151, v4
	v_mul_f32_e32 v164, v4, v34
	v_and_b32_e32 v4, 0xffff0000, v96
	s_waitcnt lgkmcnt(0)
	v_add_f32_e32 v40, v32, v33
	global_load_dwordx4 v[32:35], v76, s[12:13] offset:1648
	global_load_dwordx4 v[36:39], v76, s[12:13] offset:1632
	ds_bpermute_b32 v41, v184, v40
	v_add_f32_e32 v5, v151, v5
	v_mul_f32_e32 v96, v5, v4
	s_waitcnt lgkmcnt(0)
	s_barrier
; __device__ __forceinline__ float bf_lo(unsigned w) { return __uint_as_float(w << 16); }
; __device__ __forceinline__ float bf_hi(unsigned w) { return __uint_as_float(w & 0xffff0000u); }
; __device__ __forceinline__ bf16 f2bf(float f) { return (bf16)(cvt_pk_nv(f, 0.f) & 0xffffu); }
;     __device__ __forceinline__ float* out() const { return (float*)karg_in(33); }
; __device__ __forceinline__ void gmlp_tile(const Ctx& C, int T, LAS unsigned char* lds, int wave, int lane, int tid) {
;     ...
;         __syncthreads();
;         {
;             float v[32]; float s = 0.f;
; #pragma unroll
;             for (int i = 0; i < 4; ++i) { const v4u w = vraw[i];
;                 v[8 * i + 0] = bf_lo(w.x); v[8 * i + 1] = bf_hi(w.x); v[8 * i + 2] = bf_lo(w.y); v[8 * i + 3] = bf_hi(w.y);
;                 v[8 * i + 4] = bf_lo(w.z); v[8 * i + 5] = bf_hi(w.z); v[8 * i + 6] = bf_lo(w.w); v[8 * i + 7] = bf_hi(w.w); }
;             if (h < 3) {
; #pragma unroll
;                 for (int i = 0; i < 4; ++i) vraw[i] = *(const v4u*)(vsrc + (h + 1) * 128 + 8 * i);
;             }
; #pragma unroll
;             for (int i = 0; i < 32; ++i) s += v[i] * v[i];
;             s += __shfl_xor(s, 1); s += __shfl_xor(s, 2);
;             const float r = rsqrtf(s * (1.f / 128.f) + EPS);
; #pragma unroll
;             for (int i = 0; i < 32; ++i) { v[i] = v[i] * r * gvv[i >> 2][i & 3]; VT[(q * 32 + i) * VT_STRIDE + row] = f2bf(v[i]); }
;             if (mode) { float* ov = C.out() + OFF_V_S + (size_t)row * AW + h * 128 + q * 32;
; #pragma unroll
;                 for (int i = 0; i < 8; ++i) *(v4f*)(ov + 4 * i) = (v4f){v[4 * i], v[4 * i + 1], v[4 * i + 2], v[4 * i + 3]}; }
;         }
;         __syncthreads();
	v_add_f32_e32 v4, v40, v41
	v_fmamk_f32 v4, v4, 0x3c000000, v110
	v_mul_f32_e32 v5, 0x4b800000, v4
	v_cmp_gt_f32_e32 vcc, s11, v4
	s_mov_b64 s[0:1], s[80:81]
	s_nop 0
	v_cndmask_b32_e32 v4, v4, v5, vcc
	v_rsq_f32_e32 v4, v4
	v_add_f32_e32 v8, v151, v8
	v_mul_f32_e32 v5, 0x45800000, v4
	v_cndmask_b32_e32 v4, v4, v5, vcc
	v_pk_mul_f32 v[40:41], v[4:5], v[166:167] op_sel_hi:[0,1]
	s_waitcnt vmcnt(4)
	v_pk_mul_f32 v[40:41], v[152:153], v[40:41]
	s_nop 0
	v_cvt_pk_bf16_f32 v5, v40, v77
	ds_write_b16 v123, v5
	v_cvt_pk_bf16_f32 v5, v41, v77
	ds_write_b16 v123, v5 offset:272
	v_pk_mul_f32 v[42:43], v[4:5], v[52:53] op_sel_hi:[0,1]
	v_pk_mul_f32 v[42:43], v[154:155], v[42:43]
	s_nop 0
	v_cvt_pk_bf16_f32 v5, v42, v77
	ds_write_b16 v123, v5 offset:544
	v_cvt_pk_bf16_f32 v5, v43, v77
	ds_write_b16 v123, v5 offset:816
	v_pk_mul_f32 v[52:53], v[4:5], v[172:173] op_sel_hi:[0,1]
	v_pk_mul_f32 v[28:29], v[28:29], v[52:53]
	s_nop 0
	v_cvt_pk_bf16_f32 v5, v28, v77
	ds_write_b16 v123, v5 offset:1088
	v_cvt_pk_bf16_f32 v5, v29, v77
	ds_write_b16 v123, v5 offset:1360
	v_pk_mul_f32 v[52:53], v[4:5], v[54:55] op_sel_hi:[0,1]
	v_pk_mul_f32 v[30:31], v[30:31], v[52:53]
	s_nop 0
	v_cvt_pk_bf16_f32 v5, v30, v77
	ds_write_b16 v123, v5 offset:1632
	v_cvt_pk_bf16_f32 v5, v31, v77
	ds_write_b16 v123, v5 offset:1904
	v_pk_mul_f32 v[52:53], v[4:5], v[178:179] op_sel_hi:[0,1]
	v_pk_mul_f32 v[24:25], v[24:25], v[52:53]
	s_nop 0
	v_cvt_pk_bf16_f32 v5, v24, v77
	ds_write_b16 v123, v5 offset:2176
	v_cvt_pk_bf16_f32 v5, v25, v77
	ds_write_b16 v123, v5 offset:2448
	v_pk_mul_f32 v[52:53], v[4:5], v[190:191] op_sel_hi:[0,1]
	v_pk_mul_f32 v[26:27], v[26:27], v[52:53]
	s_nop 0
	v_cvt_pk_bf16_f32 v5, v26, v77
	ds_write_b16 v123, v5 offset:2720
	v_cvt_pk_bf16_f32 v5, v27, v77
	ds_write_b16 v123, v5 offset:2992
	v_pk_mul_f32 v[52:53], v[4:5], v[192:193] op_sel_hi:[0,1]
	v_pk_mul_f32 v[20:21], v[20:21], v[52:53]
	s_nop 0
	v_cvt_pk_bf16_f32 v5, v20, v77
	ds_write_b16 v123, v5 offset:3264
	v_cvt_pk_bf16_f32 v5, v21, v77
	ds_write_b16 v123, v5 offset:3536
	v_pk_mul_f32 v[52:53], v[4:5], v[196:197] op_sel_hi:[0,1]
	v_pk_mul_f32 v[22:23], v[22:23], v[52:53]
	s_nop 0
	v_cvt_pk_bf16_f32 v5, v22, v77
	ds_write_b16 v123, v5 offset:3808
	v_cvt_pk_bf16_f32 v5, v23, v77
	ds_write_b16 v123, v5 offset:4080
	v_pk_mul_f32 v[52:53], v[4:5], v[198:199] op_sel_hi:[0,1]
	s_waitcnt vmcnt(2)
	v_pk_mul_f32 v[52:53], v[160:161], v[52:53]
	s_nop 0
	v_cvt_pk_bf16_f32 v5, v52, v77
	ds_write_b16 v123, v5 offset:4352
	v_cvt_pk_bf16_f32 v5, v53, v77
	ds_write_b16 v123, v5 offset:4624
	v_pk_mul_f32 v[54:55], v[4:5], v[202:203] op_sel_hi:[0,1]
	v_pk_mul_f32 v[54:55], v[162:163], v[54:55]
	s_nop 0
	v_cvt_pk_bf16_f32 v5, v54, v77
	ds_write_b16 v123, v5 offset:4896
	v_cvt_pk_bf16_f32 v5, v55, v77
	ds_write_b16 v123, v5 offset:5168
	v_pk_mul_f32 v[152:153], v[4:5], v[204:205] op_sel_hi:[0,1]
	v_pk_mul_f32 v[152:153], v[156:157], v[152:153]
	s_nop 0
	v_cvt_pk_bf16_f32 v5, v152, v77
	ds_write_b16 v123, v5 offset:5440
	v_cvt_pk_bf16_f32 v5, v153, v77
	ds_write_b16 v123, v5 offset:5712
	v_pk_mul_f32 v[154:155], v[4:5], v[208:209] op_sel_hi:[0,1]
	v_pk_mul_f32 v[154:155], v[158:159], v[154:155]
	s_nop 0
	v_cvt_pk_bf16_f32 v5, v154, v77
	ds_write_b16 v123, v5 offset:5984
	v_cvt_pk_bf16_f32 v5, v155, v77
	ds_write_b16 v123, v5 offset:6256
	v_pk_mul_f32 v[156:157], v[4:5], v[210:211] op_sel_hi:[0,1]
	s_waitcnt vmcnt(0)
	v_pk_mul_f32 v[36:37], v[36:37], v[156:157]
	s_nop 0
	v_cvt_pk_bf16_f32 v5, v36, v77
	ds_write_b16 v123, v5 offset:6528
	v_cvt_pk_bf16_f32 v5, v37, v77
	ds_write_b16 v123, v5 offset:6800
	v_pk_mul_f32 v[156:157], v[4:5], v[214:215] op_sel_hi:[0,1]
	v_pk_mul_f32 v[38:39], v[38:39], v[156:157]
	s_nop 0
	v_cvt_pk_bf16_f32 v5, v38, v77
	ds_write_b16 v123, v5 offset:7072
	v_cvt_pk_bf16_f32 v5, v39, v77
	ds_write_b16 v123, v5 offset:7344
	v_pk_mul_f32 v[18:19], v[4:5], v[18:19] op_sel_hi:[0,1]
	v_pk_mul_f32 v[32:33], v[32:33], v[18:19] op_sel:[0,1] op_sel_hi:[1,0]
	s_nop 0
	v_cvt_pk_bf16_f32 v5, v32, v77
	ds_write_b16 v123, v5 offset:7616
	v_cvt_pk_bf16_f32 v5, v33, v77
	ds_write_b16 v123, v5 offset:7888
	v_pk_mul_f32 v[4:5], v[4:5], v[16:17] op_sel_hi:[0,1]
	v_pk_mul_f32 v[34:35], v[34:35], v[4:5] op_sel:[0,1] op_sel_hi:[1,0]
	v_add_f32_e32 v5, v151, v6
	v_cvt_pk_bf16_f32 v4, v34, v77
	ds_write_b16 v123, v4 offset:8160
	v_cvt_pk_bf16_f32 v4, v35, v77
	ds_write_b16 v123, v4 offset:8432
	s_load_dwordx2 s[0:1], s[0:1], 0x108
	v_lshlrev_b32_e32 v4, 16, v97
	v_mul_f32_e32 v123, v5, v4
	v_and_b32_e32 v6, 0xffff0000, v97
	s_waitcnt lgkmcnt(0)
	v_lshl_add_u64 v[4:5], s[0:1], 0, v[82:83]
	v_lshl_add_u64 v[4:5], v[4:5], 0, v[76:77]
	s_mov_b64 s[0:1], 0x80a8600
	v_lshl_add_u64 v[16:17], v[4:5], 0, s[0:1]
	v_add_co_u32_e32 v4, vcc, s16, v4
	s_nop 1
	v_addc_co_u32_e32 v5, vcc, 0, v5, vcc
	global_store_dwordx4 v[4:5], v[40:43], off offset:1536
	global_store_dwordx4 v[16:17], v[28:31], off offset:16
	global_store_dwordx4 v[16:17], v[24:27], off offset:32
	global_store_dwordx4 v[16:17], v[20:23], off offset:48
	global_store_dwordx4 v[16:17], v[52:55], off offset:64
	global_store_dwordx4 v[16:17], v[152:155], off offset:80
	global_store_dwordx4 v[16:17], v[36:39], off offset:96
	global_store_dwordx4 v[16:17], v[32:35], off offset:112
	s_barrier
; __device__ __forceinline__ float bf_lo(unsigned w) { return __uint_as_float(w << 16); }
; __device__ __forceinline__ float bf_hi(unsigned w) { return __uint_as_float(w & 0xffff0000u); }
; #define LAS __attribute__((address_space(3)))
; __device__ __forceinline__ unsigned cvt_pk_nv(float lo, float hi) { unsigned r; asm("v_cvt_pk_bf16_f32 %0, %1, %2" : "=v"(r) : "v"(lo), "v"(hi)); return r; }
; __device__ __forceinline__ void gmlp_tile(const Ctx& C, int T, LAS unsigned char* lds, int wave, int lane, int tid) {
;     ...
; #pragma unroll
;         for (int dbi = 0; dbi < 2; ++dbi) {
;             const int db = 2 * dh + dbi;
;             v16f acc;
; #pragma unroll
;             for (int r = 0; r < 16; ++r) acc[r] = 0.f;
; #pragma unroll
;             for (int ks = 0; ks < 8; ++ks) {
;                 const bfx8 va = *(const LAS bfx8*)(VT + (32 * db + tl) * VT_STRIDE + 16 * ks + 8 * hh);
;                 acc = __builtin_amdgcn_mfma_f32_32x32x16_bf16(va, wf[ks], acc, 0, 0, 0);
;             }
; #pragma unroll
;             for (int rg = 0; rg < 4; ++rg) {
;                 const v2u u2 = uw[dbi][rg];
;                 const float o0 = bf_lo(u2.x) * (acc[4 * rg + 0] + bias), o1 = bf_hi(u2.x) * (acc[4 * rg + 1] + bias);
;                 const float o2 = bf_lo(u2.y) * (acc[4 * rg + 2] + bias), o3 = bf_hi(u2.y) * (acc[4 * rg + 3] + bias);
;                 ssq += (o0 * o0 + o1 * o1) + (o2 * o2 + o3 * o3);
;                 outp[h][dbi][2 * rg] = cvt_pk_nv(o0, o1); outp[h][dbi][2 * rg + 1] = cvt_pk_nv(o2, o3);
;             }
	ds_read_b128 v[16:19], v122
	v_add_f32_e32 v4, v151, v7
	v_mul_f32_e32 v32, v4, v6
	v_mul_f32_e32 v4, v96, v96
	v_mul_f32_e32 v5, v32, v32
	v_fmac_f32_e32 v4, v164, v164
	v_fmac_f32_e32 v5, v123, v123
	v_add_f32_e32 v33, v4, v5
	ds_read_b128 v[4:7], v122 offset:32
	s_waitcnt lgkmcnt(1)
	v_mfma_f32_32x32x16_bf16 v[16:31], v[16:19], v[0:3], 0
	ds_read_b128 v[36:39], v122 offset:64
	v_lshlrev_b32_e32 v34, 16, v92
	v_mul_f32_e32 v34, v8, v34
	v_and_b32_e32 v8, 0xffff0000, v93
	v_add_f32_e32 v33, v33, v189
	ds_read_b128 v[52:55], v122 offset:8768
	v_cmp_gt_u32_e32 vcc, 32, v108
	s_waitcnt lgkmcnt(2)
	v_mfma_f32_32x32x16_bf16 v[16:31], v[4:7], v[72:75], v[16:31]
	v_and_b32_e32 v4, 0xffff0000, v92
	v_add_f32_e32 v5, v151, v9
	v_mul_f32_e32 v40, v5, v4
	v_lshlrev_b32_e32 v4, 16, v93
	v_add_f32_e32 v5, v151, v10
	v_mul_f32_e32 v41, v5, v4
	ds_read_b128 v[4:7], v122 offset:96
	s_waitcnt lgkmcnt(2)
	v_mfma_f32_32x32x16_bf16 v[16:31], v[36:39], v[68:71], v[16:31]
	v_add_f32_e32 v9, v151, v11
	v_mul_f32_e32 v37, v9, v8
	ds_read_b128 v[8:11], v122 offset:128
	v_mul_f32_e32 v36, v40, v40
	v_mul_f32_e32 v38, v37, v37
	v_fmac_f32_e32 v36, v34, v34
	v_fmac_f32_e32 v38, v41, v41
	s_waitcnt lgkmcnt(1)
	v_mfma_f32_32x32x16_bf16 v[16:31], v[4:7], v[64:67], v[16:31]
	v_add_f32_e32 v4, v36, v38
	v_add_f32_e32 v38, v4, v33
	ds_read_b128 v[4:7], v122 offset:160
	v_cvt_pk_bf16_f32 v36, v34, v40
	v_lshlrev_b32_e32 v34, 16, v88
	v_cvt_pk_bf16_f32 v33, v41, v37
	v_cvt_pk_bf16_f32 v35, v164, v96
	s_waitcnt lgkmcnt(1)
	v_mfma_f32_32x32x16_bf16 v[16:31], v[8:11], v[60:63], v[16:31]
	v_add_f32_e32 v8, v151, v12
	v_mul_f32_e32 v12, v8, v34
	v_and_b32_e32 v8, 0xffff0000, v88
	v_add_f32_e32 v9, v151, v13
	v_mul_f32_e32 v13, v9, v8
	ds_read_b128 v[8:11], v122 offset:192
	v_lshlrev_b32_e32 v34, 16, v89
	s_waitcnt lgkmcnt(1)
	v_mfma_f32_32x32x16_bf16 v[16:31], v[4:7], v[56:59], v[16:31]
	v_add_f32_e32 v4, v151, v14
	v_mul_f32_e32 v14, v4, v34
	v_and_b32_e32 v4, 0xffff0000, v89
	v_add_f32_e32 v5, v151, v15
	v_mul_f32_e32 v15, v5, v4
	ds_read_b128 v[4:7], v122 offset:224
	v_mul_f32_e32 v34, v13, v13
	s_waitcnt lgkmcnt(1)
	v_mfma_f32_32x32x16_bf16 v[16:31], v[8:11], v[48:51], v[16:31]
	v_mul_f32_e32 v8, v15, v15
	v_fmac_f32_e32 v34, v12, v12
	v_fmac_f32_e32 v8, v14, v14
	v_add_f32_e32 v8, v34, v8
	v_add_f32_e32 v8, v8, v38
	ds_read_b128 v[38:41], v122 offset:8736
	v_cvt_pk_bf16_f32 v37, v12, v13
	s_waitcnt lgkmcnt(1)
	v_mfma_f32_32x32x16_bf16 v[16:31], v[4:7], v[44:47], v[16:31]
	v_lshlrev_b32_e32 v4, 16, v102
	v_cvt_pk_bf16_f32 v34, v14, v15
	v_cvt_pk_bf16_f32 v32, v123, v32
	s_nop 10
	v_add_f32_e32 v5, v124, v16
	v_mul_f32_e32 v4, v5, v4
	v_and_b32_e32 v5, 0xffff0000, v102
	v_add_f32_e32 v6, v124, v17
	v_mul_f32_e32 v5, v6, v5
	v_lshlrev_b32_e32 v6, 16, v103
	v_add_f32_e32 v7, v124, v18
	v_mul_f32_e32 v6, v7, v6
	v_and_b32_e32 v7, 0xffff0000, v103
	v_add_f32_e32 v9, v124, v19
	v_mul_f32_e32 v7, v9, v7
	v_mul_f32_e32 v9, v5, v5
	v_fmac_f32_e32 v9, v4, v4
	v_cvt_pk_bf16_f32 v17, v4, v5
	v_lshlrev_b32_e32 v4, 16, v100
	v_add_f32_e32 v5, v124, v20
	v_mul_f32_e32 v19, v5, v4
	v_and_b32_e32 v4, 0xffff0000, v100
	v_add_f32_e32 v5, v124, v21
	v_mul_f32_e32 v10, v7, v7
	v_mul_f32_e32 v20, v5, v4
	v_lshlrev_b32_e32 v4, 16, v101
	v_add_f32_e32 v5, v124, v22
	v_fmac_f32_e32 v10, v6, v6
	v_cvt_pk_bf16_f32 v16, v6, v7
	v_mul_f32_e32 v21, v5, v4
	ds_read_b128 v[4:7], v122 offset:8704
	v_add_f32_e32 v9, v9, v10
	v_add_f32_e32 v18, v8, v9
	v_and_b32_e32 v8, 0xffff0000, v101
	v_add_f32_e32 v9, v124, v23
	v_mul_f32_e32 v22, v9, v8
	v_mul_f32_e32 v8, v20, v20
	v_mul_f32_e32 v9, v22, v22
	v_fmac_f32_e32 v8, v19, v19
	v_fmac_f32_e32 v9, v21, v21
	v_add_f32_e32 v23, v8, v9
	s_waitcnt lgkmcnt(0)
	v_mfma_f32_32x32x16_bf16 v[0:15], v[4:7], v[0:3], 0
	v_add_f32_e32 v42, v23, v18
	v_cvt_pk_bf16_f32 v20, v19, v20
	v_cvt_pk_bf16_f32 v18, v21, v22
	v_lshlrev_b32_e32 v19, 16, v98
	v_add_f32_e32 v21, v124, v24
	v_mul_f32_e32 v19, v21, v19
	v_and_b32_e32 v21, 0xffff0000, v98
	v_mfma_f32_32x32x16_bf16 v[0:15], v[38:41], v[72:75], v[0:15]
	v_add_f32_e32 v22, v124, v25
	v_mul_f32_e32 v21, v22, v21
	v_lshlrev_b32_e32 v22, 16, v99
	v_add_f32_e32 v23, v124, v26
	v_mul_f32_e32 v26, v23, v22
	ds_read_b128 v[22:25], v122 offset:8800
	v_and_b32_e32 v38, 0xffff0000, v99
	v_mfma_f32_32x32x16_bf16 v[0:15], v[52:55], v[68:71], v[0:15]
	v_add_f32_e32 v27, v124, v27
	v_mul_f32_e32 v27, v27, v38
	ds_read_b128 v[38:41], v122 offset:8832
	v_mul_f32_e32 v43, v21, v21
	v_mul_f32_e32 v52, v27, v27
	v_fmac_f32_e32 v43, v19, v19
	v_fmac_f32_e32 v52, v26, v26
	s_waitcnt lgkmcnt(1)
; __device__ __forceinline__ float bf_lo(unsigned w) { return __uint_as_float(w << 16); }
; __device__ __forceinline__ float bf_hi(unsigned w) { return __uint_as_float(w & 0xffff0000u); }
; #define LAS __attribute__((address_space(3)))
; __device__ __forceinline__ unsigned cvt_pk_nv(float lo, float hi) { unsigned r; asm("v_cvt_pk_bf16_f32 %0, %1, %2" : "=v"(r) : "v"(lo), "v"(hi)); return r; }
; __device__ __forceinline__ void gmlp_tile(const Ctx& C, int T, LAS unsigned char* lds, int wave, int lane, int tid) {
;     ...
; #pragma unroll
;         for (int dbi = 0; dbi < 2; ++dbi) {
;             const int db = 2 * dh + dbi;
;             v16f acc;
; #pragma unroll
;             for (int r = 0; r < 16; ++r) acc[r] = 0.f;
; #pragma unroll
;             for (int ks = 0; ks < 8; ++ks) {
;                 const bfx8 va = *(const LAS bfx8*)(VT + (32 * db + tl) * VT_STRIDE + 16 * ks + 8 * hh);
;                 acc = __builtin_amdgcn_mfma_f32_32x32x16_bf16(va, wf[ks], acc, 0, 0, 0);
;             }
; #pragma unroll
;             for (int rg = 0; rg < 4; ++rg) {
;                 const v2u u2 = uw[dbi][rg];
;                 const float o0 = bf_lo(u2.x) * (acc[4 * rg + 0] + bias), o1 = bf_hi(u2.x) * (acc[4 * rg + 1] + bias);
;                 const float o2 = bf_lo(u2.y) * (acc[4 * rg + 2] + bias), o3 = bf_hi(u2.y) * (acc[4 * rg + 3] + bias);
;                 ssq += (o0 * o0 + o1 * o1) + (o2 * o2 + o3 * o3);
;                 outp[h][dbi][2 * rg] = cvt_pk_nv(o0, o1); outp[h][dbi][2 * rg + 1] = cvt_pk_nv(o2, o3);
;             }
;         }
;     }
;     ssq += __shfl_xor(ssq, 32);
;     if (hh == 0) SSQ[t * 2 + dh] = ssq;
	v_mfma_f32_32x32x16_bf16 v[0:15], v[22:25], v[64:67], v[0:15]
	v_add_f32_e32 v22, v43, v52
	v_add_f32_e32 v42, v22, v42
	ds_read_b128 v[22:25], v122 offset:8864
	v_cvt_pk_bf16_f32 v21, v19, v21
	v_cvt_pk_bf16_f32 v19, v26, v27
	v_lshlrev_b32_e32 v26, 16, v94
	v_add_f32_e32 v27, v124, v28
	s_waitcnt lgkmcnt(1)
	v_mfma_f32_32x32x16_bf16 v[0:15], v[38:41], v[60:63], v[0:15]
	v_mul_f32_e32 v43, v27, v26
	v_and_b32_e32 v26, 0xffff0000, v94
	v_add_f32_e32 v27, v124, v29
	v_mul_f32_e32 v52, v27, v26
	ds_read_b128 v[26:29], v122 offset:8896
	v_lshlrev_b32_e32 v38, 16, v95
	s_waitcnt lgkmcnt(1)
	v_mfma_f32_32x32x16_bf16 v[0:15], v[22:25], v[56:59], v[0:15]
	v_add_f32_e32 v22, v124, v30
	v_mul_f32_e32 v22, v22, v38
	ds_read_b128 v[38:41], v122 offset:8928
	v_and_b32_e32 v23, 0xffff0000, v95
	v_add_f32_e32 v24, v124, v31
	v_mul_f32_e32 v24, v24, v23
	v_mul_f32_e32 v25, v24, v24
	s_waitcnt lgkmcnt(1)
	v_mfma_f32_32x32x16_bf16 v[0:15], v[26:29], v[48:51], v[0:15]
	v_fmac_f32_e32 v25, v22, v22
	v_cvt_pk_bf16_f32 v22, v22, v24
	v_lshlrev_b32_e32 v24, 16, v90
	v_mul_f32_e32 v23, v52, v52
	v_fmac_f32_e32 v23, v43, v43
	v_add_f32_e32 v23, v23, v25
	v_add_f32_e32 v25, v23, v42
	s_waitcnt lgkmcnt(0)
	v_mfma_f32_32x32x16_bf16 v[0:15], v[38:41], v[44:47], v[0:15]
	v_cvt_pk_bf16_f32 v23, v43, v52
	s_nop 11
	v_add_f32_e32 v0, v124, v0
	v_mul_f32_e32 v0, v0, v24
	v_and_b32_e32 v24, 0xffff0000, v90
	v_add_f32_e32 v1, v124, v1
	v_mul_f32_e32 v1, v1, v24
	v_lshlrev_b32_e32 v24, 16, v91
	v_add_f32_e32 v2, v124, v2
	v_mul_f32_e32 v2, v2, v24
	v_and_b32_e32 v24, 0xffff0000, v91
	v_add_f32_e32 v3, v124, v3
	v_mul_f32_e32 v24, v3, v24
	v_mul_f32_e32 v3, v1, v1
	v_mul_f32_e32 v26, v24, v24
	v_fmac_f32_e32 v3, v0, v0
	v_fmac_f32_e32 v26, v2, v2
	v_add_f32_e32 v3, v3, v26
	v_add_f32_e32 v25, v25, v3
	v_cvt_pk_bf16_f32 v3, v0, v1
	v_lshlrev_b32_e32 v0, 16, v86
	v_add_f32_e32 v1, v124, v4
	v_mul_f32_e32 v0, v1, v0
	v_and_b32_e32 v1, 0xffff0000, v86
	v_add_f32_e32 v4, v124, v5
	v_mul_f32_e32 v1, v4, v1
	v_lshlrev_b32_e32 v4, 16, v87
	v_add_f32_e32 v5, v124, v6
	v_mul_f32_e32 v4, v5, v4
	v_and_b32_e32 v5, 0xffff0000, v87
	v_add_f32_e32 v6, v124, v7
	v_mul_f32_e32 v6, v6, v5
	v_mul_f32_e32 v5, v1, v1
	v_mul_f32_e32 v7, v6, v6
	v_fmac_f32_e32 v5, v0, v0
	v_fmac_f32_e32 v7, v4, v4
	v_add_f32_e32 v5, v5, v7
	v_add_f32_e32 v7, v5, v25
	v_cvt_pk_bf16_f32 v5, v0, v1
	v_lshlrev_b32_e32 v0, 16, v84
	v_add_f32_e32 v1, v124, v8
	v_cvt_pk_bf16_f32 v4, v4, v6
	v_mul_f32_e32 v0, v1, v0
	v_and_b32_e32 v1, 0xffff0000, v84
	v_add_f32_e32 v6, v124, v9
	v_mul_f32_e32 v1, v6, v1
	v_lshlrev_b32_e32 v6, 16, v85
	v_add_f32_e32 v8, v124, v10
	v_mul_f32_e32 v6, v8, v6
	v_and_b32_e32 v8, 0xffff0000, v85
	v_add_f32_e32 v9, v124, v11
	v_mul_f32_e32 v8, v9, v8
	v_mul_f32_e32 v9, v1, v1
	v_mul_f32_e32 v10, v8, v8
	v_fmac_f32_e32 v9, v0, v0
	v_fmac_f32_e32 v10, v6, v6
	v_add_f32_e32 v9, v9, v10
	v_add_f32_e32 v9, v9, v7
	v_cvt_pk_bf16_f32 v7, v0, v1
	v_lshlrev_b32_e32 v0, 16, v78
	v_add_f32_e32 v1, v124, v12
	v_cvt_pk_bf16_f32 v6, v6, v8
	v_mul_f32_e32 v0, v1, v0
	v_and_b32_e32 v1, 0xffff0000, v78
	v_add_f32_e32 v8, v124, v13
	v_mul_f32_e32 v8, v8, v1
	v_lshlrev_b32_e32 v1, 16, v79
	v_add_f32_e32 v10, v124, v14
	v_mul_f32_e32 v11, v10, v1
	v_and_b32_e32 v1, 0xffff0000, v79
	v_add_f32_e32 v10, v124, v15
	v_mul_f32_e32 v12, v10, v1
	v_mul_f32_e32 v1, v8, v8
	v_mul_f32_e32 v10, v12, v12
	v_fmac_f32_e32 v1, v0, v0
	v_fmac_f32_e32 v10, v11, v11
	v_add_f32_e32 v1, v1, v10
	v_add_f32_e32 v1, v1, v9
	ds_bpermute_b32 v10, v188, v1
	v_cvt_pk_bf16_f32 v9, v0, v8
	v_lshlrev_b32_e32 v0, 3, v109
	v_cvt_pk_bf16_f32 v2, v2, v24
	v_cvt_pk_bf16_f32 v8, v11, v12
	s_and_saveexec_b64 s[12:13], vcc
	s_cbranch_execz .LBB0_683
	s_lshl_b32 s0, s15, 2
	s_add_i32 s0, s0, 0
	s_waitcnt lgkmcnt(0)
	v_add_f32_e32 v1, v1, v10
	v_add_u32_e32 v10, s0, v0
	ds_write_b32 v10, v1 offset:34816
